# K-loop LDS-DMA loads use the SGPR-base plus 32-bit VGPR-offset form, dropping the per-load 64-bit VALU address add
# speedup vs baseline: 1.0085x; 1.0008x over previous
; #define PG8_STAGE(bufoff, gbase, voff) do { _Pragma("unroll") for (int _i = 0; _i < 2; ++_i) \
;         __builtin_amdgcn_global_load_lds((const unsigned*)((const char*)(gbase) + (voff)[_i]), (PG8_LAS unsigned*)(lds + (bufoff) + ldsw + _i * 8192), 16, 0, 0); } while (0)
; #define PG8_LDA(dst, b, h) do { _Pragma("unroll") for (int m = 0; m < 4; ++m) _Pragma("unroll") for (int k = 0; k < 2; ++k) dst[m][k] = *(const PG8_LAS bf16x8*)(lds + PG8_SA(b, h) + aoff + m * 2048 + k * 1024); } while (0)
; #define PG8_LDB(dst, b, h) do { _Pragma("unroll") for (int n = 0; n < 2; ++n) _Pragma("unroll") for (int k = 0; k < 2; ++k) dst[n][k] = *(const PG8_LAS bf16x8*)(lds + PG8_SB(b, h) + boff + n * 2048 + k * 1024); } while (0)
; #define PG8_MMA(ai, bj, At, Bt) do { __builtin_amdgcn_s_setprio(1); _Pragma("unroll") for (int m = 0; m < 4; ++m) _Pragma("unroll") for (int n = 0; n < 2; ++n) _Pragma("unroll") for (int k = 0; k < 2; ++k) \
;         acc[ai][bj][m][n] = __builtin_amdgcn_mfma_f32_16x16x32_bf16(Bt[n][k], At[m][k], acc[ai][bj][m][n], 0, 0, 0); __builtin_amdgcn_s_setprio(0); } while (0)
; #define PG8_WAIT_L(n) asm volatile("s_waitcnt lgkmcnt(" #n ")" ::: "memory")
; #define PG8_BAR __builtin_amdgcn_s_barrier()
; #define PG8_SCHED __builtin_amdgcn_sched_barrier(0)
; template <class Epi, class Sched>
; __device__ __forceinline__ void gemm_phase(PG8_LAS unsigned char* lds, const Gemm g, const Sched& S, const Epi& E) {
;     ...
;         for (int t = 0; t < nt; t += 2) {
;             const bool last = (t == nt - 2);
;             const char* a1 = cA + (size_t)(t + 1) * kstep;
;             const char* a2 = last ? nA : cA + (size_t)(t + 2) * kstep; const char* b2 = last ? nB : cB + (size_t)(t + 2) * kstepB;
;             const char* a3 = a2 + kstep; const char* b3 = b2 + kstepB;
;             if (last && has_next) S.a_ready(nxt);
;             PG8_LDB(B0, 0, 0); PG8_SCHED; PG8_LDA(At, 0, 0); PG8_STAGE(PG8_SA(1, 1), a1 + hstep, voffA);
;             PG8_WAIT_L(8); PG8_BAR; PG8_WAIT_L(0); PG8_MMA(0, 0, At, B0); PG8_BAR; PG8_SCHED;
;             PG8_LDB(B1, 0, 1); PG8_STAGE(PG8_SB(0, 0), b2, voffB);
;             PG8_BAR; PG8_WAIT_L(0); PG8_MMA(0, 1, At, B1); PG8_BAR;
;             PG8_LDA(At, 0, 1); PG8_STAGE(PG8_SA(0, 0), a2, voffA);
;             PG8_BAR; PG8_WAIT_L(0); PG8_MMA(1, 0, At, B0); PG8_BAR; PG8_SCHED;
;             PG8_STAGE(PG8_SB(0, 1), b2 + hstepB, voffB);
.Lhalf_skip_y_0:
.LBB0_79:
	ds_read_b128 v[152:155], v149
	ds_read_b128 v[156:159], v149 offset:1024
	ds_read_b128 v[160:163], v149 offset:2048
	ds_read_b128 v[164:167], v149 offset:3072
	s_add_u32 s24, s22, 0xfff80080
	s_addc_u32 s25, s23, -1
	s_cmp_eq_u32 s61, 28
	s_cselect_b32 s27, s13, s25
	s_cselect_b32 s26, s57, s24
	s_cselect_b32 s25, s15, s60
	s_cselect_b32 s24, s58, s59
	s_add_i32 m0, s21, 0xc000
	ds_read_b128 v[168:171], v150
	ds_read_b128 v[172:175], v150 offset:1024
	ds_read_b128 v[176:179], v150 offset:2048
	ds_read_b128 v[180:183], v150 offset:3072
	ds_read_b128 v[184:187], v150 offset:4096
	ds_read_b128 v[188:191], v150 offset:5120
	ds_read_b128 v[192:195], v150 offset:6144
	ds_read_b128 v[196:199], v150 offset:7168
	global_load_lds_dwordx4 v136, s[22:23]
	s_add_i32 m0, s21, 0xe000
	s_nop 0
	global_load_lds_dwordx4 v138, s[22:23]
	s_add_i32 s62, s53, s38
	s_mov_b32 m0, s62
	ds_read_b128 v[200:203], v151
	ds_read_b128 v[204:207], v151 offset:1024
	ds_read_b128 v[208:211], v151 offset:2048
	ds_read_b128 v[212:215], v151 offset:3072
	s_waitcnt vmcnt(8)
	s_waitcnt lgkmcnt(0)
	s_barrier
	v_mfma_f32_16x16x32_bf16 v[124:127], v[152:155], v[168:171], v[124:127]
	v_mfma_f32_16x16x32_bf16 v[120:123], v[160:163], v[168:171], v[120:123]
	v_mfma_f32_16x16x32_bf16 v[108:111], v[152:155], v[176:179], v[108:111]
	v_mfma_f32_16x16x32_bf16 v[104:107], v[160:163], v[176:179], v[104:107]
	v_mfma_f32_16x16x32_bf16 v[92:95], v[152:155], v[184:187], v[92:95]
	v_mfma_f32_16x16x32_bf16 v[88:91], v[160:163], v[184:187], v[88:91]
	v_mfma_f32_16x16x32_bf16 v[76:79], v[152:155], v[192:195], v[76:79]
	v_mfma_f32_16x16x32_bf16 v[72:75], v[160:163], v[192:195], v[72:75]
	v_mfma_f32_16x16x32_bf16 v[124:127], v[156:159], v[172:175], v[124:127]
	v_mfma_f32_16x16x32_bf16 v[120:123], v[164:167], v[172:175], v[120:123]
	v_mfma_f32_16x16x32_bf16 v[108:111], v[156:159], v[180:183], v[108:111]
	v_mfma_f32_16x16x32_bf16 v[104:107], v[164:167], v[180:183], v[104:107]
	v_mfma_f32_16x16x32_bf16 v[92:95], v[156:159], v[188:191], v[92:95]
	v_mfma_f32_16x16x32_bf16 v[88:91], v[164:167], v[188:191], v[88:91]
	v_mfma_f32_16x16x32_bf16 v[76:79], v[156:159], v[196:199], v[76:79]
	v_mfma_f32_16x16x32_bf16 v[72:75], v[164:167], v[196:199], v[72:75]
	v_mfma_f32_16x16x32_bf16 v[116:119], v[200:203], v[168:171], v[116:119]
	v_mfma_f32_16x16x32_bf16 v[112:115], v[208:211], v[168:171], v[112:115]
	v_mfma_f32_16x16x32_bf16 v[100:103], v[200:203], v[176:179], v[100:103]
	v_mfma_f32_16x16x32_bf16 v[96:99], v[208:211], v[176:179], v[96:99]
	v_mfma_f32_16x16x32_bf16 v[84:87], v[200:203], v[184:187], v[84:87]
	v_mfma_f32_16x16x32_bf16 v[80:83], v[208:211], v[184:187], v[80:83]
	v_mfma_f32_16x16x32_bf16 v[68:71], v[200:203], v[192:195], v[68:71]
	v_mfma_f32_16x16x32_bf16 v[64:67], v[208:211], v[192:195], v[64:67]
	v_mfma_f32_16x16x32_bf16 v[116:119], v[204:207], v[172:175], v[116:119]
	v_mfma_f32_16x16x32_bf16 v[112:115], v[212:215], v[172:175], v[112:115]
	v_mfma_f32_16x16x32_bf16 v[100:103], v[204:207], v[180:183], v[100:103]
	v_mfma_f32_16x16x32_bf16 v[96:99], v[212:215], v[180:183], v[96:99]
	v_mfma_f32_16x16x32_bf16 v[84:87], v[204:207], v[188:191], v[84:87]
	v_mfma_f32_16x16x32_bf16 v[80:83], v[212:215], v[188:191], v[80:83]
	v_mfma_f32_16x16x32_bf16 v[68:71], v[204:207], v[196:199], v[68:71]
	v_mfma_f32_16x16x32_bf16 v[64:67], v[212:215], v[196:199], v[64:67]
	s_barrier
	global_load_lds_dwordx4 v128, s[24:25]
	s_add_i32 m0, s62, 0x2000
	s_nop 0
	global_load_lds_dwordx4 v130, s[24:25]
	s_mov_b32 m0, s21
	v_lshl_add_u64 v[144:145], s[26:27], 0, v[134:135]
	ds_read_b128 v[168:171], v150 offset:16384
	ds_read_b128 v[172:175], v150 offset:17408
	ds_read_b128 v[176:179], v150 offset:18432
	ds_read_b128 v[180:183], v150 offset:19456
	ds_read_b128 v[184:187], v150 offset:20480
	ds_read_b128 v[188:191], v150 offset:21504
	ds_read_b128 v[192:195], v150 offset:22528
	ds_read_b128 v[196:199], v150 offset:23552
	global_load_lds_dwordx4 v[144:145], off
	v_lshl_add_u64 v[216:217], s[26:27], 0, v[132:133]
	s_mov_b32 m0, s46
	s_nop 0
	global_load_lds_dwordx4 v[216:217], off
	s_add_u32 s62, s24, 0x4000
	s_addc_u32 s63, s25, 0
	s_add_i32 s64, s54, s38
	s_mov_b32 m0, s64
	s_nop 0
	global_load_lds_dwordx4 v128, s[62:63]
	s_add_i32 m0, s64, 0x2000
	s_nop 0
	global_load_lds_dwordx4 v130, s[62:63]
	s_waitcnt vmcnt(8)
	s_waitcnt lgkmcnt(0)
	s_barrier
	v_mfma_f32_16x16x32_bf16 v[60:63], v[152:155], v[168:171], v[60:63]
	v_mfma_f32_16x16x32_bf16 v[56:59], v[160:163], v[168:171], v[56:59]
	v_mfma_f32_16x16x32_bf16 v[44:47], v[152:155], v[176:179], v[44:47]
	v_mfma_f32_16x16x32_bf16 v[40:43], v[160:163], v[176:179], v[40:43]
	v_mfma_f32_16x16x32_bf16 v[28:31], v[152:155], v[184:187], v[28:31]
	v_mfma_f32_16x16x32_bf16 v[24:27], v[160:163], v[184:187], v[24:27]
	v_mfma_f32_16x16x32_bf16 v[12:15], v[152:155], v[192:195], v[12:15]
	v_mfma_f32_16x16x32_bf16 v[8:11], v[160:163], v[192:195], v[8:11]
	v_mfma_f32_16x16x32_bf16 v[60:63], v[156:159], v[172:175], v[60:63]
	v_mfma_f32_16x16x32_bf16 v[56:59], v[164:167], v[172:175], v[56:59]
	v_mfma_f32_16x16x32_bf16 v[44:47], v[156:159], v[180:183], v[44:47]
	v_mfma_f32_16x16x32_bf16 v[40:43], v[164:167], v[180:183], v[40:43]
	v_mfma_f32_16x16x32_bf16 v[28:31], v[156:159], v[188:191], v[28:31]
	v_mfma_f32_16x16x32_bf16 v[24:27], v[164:167], v[188:191], v[24:27]
	v_mfma_f32_16x16x32_bf16 v[12:15], v[156:159], v[196:199], v[12:15]
	v_mfma_f32_16x16x32_bf16 v[8:11], v[164:167], v[196:199], v[8:11]
	v_mfma_f32_16x16x32_bf16 v[52:55], v[200:203], v[168:171], v[52:55]
	v_mfma_f32_16x16x32_bf16 v[48:51], v[208:211], v[168:171], v[48:51]
	v_mfma_f32_16x16x32_bf16 v[36:39], v[200:203], v[176:179], v[36:39]
	v_mfma_f32_16x16x32_bf16 v[32:35], v[208:211], v[176:179], v[32:35]
	v_mfma_f32_16x16x32_bf16 v[20:23], v[200:203], v[184:187], v[20:23]
	v_mfma_f32_16x16x32_bf16 v[16:19], v[208:211], v[184:187], v[16:19]
	v_mfma_f32_16x16x32_bf16 v[4:7], v[200:203], v[192:195], v[4:7]
	v_mfma_f32_16x16x32_bf16 v[0:3], v[208:211], v[192:195], v[0:3]
	v_mfma_f32_16x16x32_bf16 v[52:55], v[204:207], v[172:175], v[52:55]
	v_mfma_f32_16x16x32_bf16 v[48:51], v[212:215], v[172:175], v[48:51]
	v_mfma_f32_16x16x32_bf16 v[36:39], v[204:207], v[180:183], v[36:39]
	v_mfma_f32_16x16x32_bf16 v[32:35], v[212:215], v[180:183], v[32:35]
	v_mfma_f32_16x16x32_bf16 v[20:23], v[204:207], v[188:191], v[20:23]
	v_mfma_f32_16x16x32_bf16 v[16:19], v[212:215], v[188:191], v[16:19]
	v_mfma_f32_16x16x32_bf16 v[4:7], v[204:207], v[196:199], v[4:7]
	v_mfma_f32_16x16x32_bf16 v[0:3], v[212:215], v[196:199], v[0:3]
	s_barrier
; #define PG8_STAGE(bufoff, gbase, voff) do { _Pragma("unroll") for (int _i = 0; _i < 2; ++_i) \
;         __builtin_amdgcn_global_load_lds((const unsigned*)((const char*)(gbase) + (voff)[_i]), (PG8_LAS unsigned*)(lds + (bufoff) + ldsw + _i * 8192), 16, 0, 0); } while (0)
; #define PG8_LDA(dst, b, h) do { _Pragma("unroll") for (int m = 0; m < 4; ++m) _Pragma("unroll") for (int k = 0; k < 2; ++k) dst[m][k] = *(const PG8_LAS bf16x8*)(lds + PG8_SA(b, h) + aoff + m * 2048 + k * 1024); } while (0)
; #define PG8_LDB(dst, b, h) do { _Pragma("unroll") for (int n = 0; n < 2; ++n) _Pragma("unroll") for (int k = 0; k < 2; ++k) dst[n][k] = *(const PG8_LAS bf16x8*)(lds + PG8_SB(b, h) + boff + n * 2048 + k * 1024); } while (0)
; #define PG8_MMA(ai, bj, At, Bt) do { __builtin_amdgcn_s_setprio(1); _Pragma("unroll") for (int m = 0; m < 4; ++m) _Pragma("unroll") for (int n = 0; n < 2; ++n) _Pragma("unroll") for (int k = 0; k < 2; ++k) \
;         acc[ai][bj][m][n] = __builtin_amdgcn_mfma_f32_16x16x32_bf16(Bt[n][k], At[m][k], acc[ai][bj][m][n], 0, 0, 0); __builtin_amdgcn_s_setprio(0); } while (0)
; #define PG8_WAIT_V(n) asm volatile("s_waitcnt vmcnt(" #n ")" ::: "memory")
; #define PG8_WAIT_L(n) asm volatile("s_waitcnt lgkmcnt(" #n ")" ::: "memory")
; #define PG8_BAR __builtin_amdgcn_s_barrier()
; #define PG8_SCHED __builtin_amdgcn_sched_barrier(0)
; template <class Epi, class Sched>
; __device__ __forceinline__ void gemm_phase(PG8_LAS unsigned char* lds, const Gemm g, const Sched& S, const Epi& E) {
;     ...
;             PG8_WAIT_V(6); PG8_BAR; PG8_MMA(1, 1, At, B1); PG8_BAR;
;             PG8_LDB(B0, 1, 0); PG8_SCHED; PG8_LDA(At, 1, 0); PG8_STAGE(PG8_SA(0, 1), a2 + hstep, voffA);
;             PG8_WAIT_L(8); PG8_BAR; PG8_WAIT_L(0); PG8_MMA(0, 0, At, B0); PG8_BAR; PG8_SCHED;
;             PG8_LDB(B1, 1, 1); PG8_STAGE(PG8_SB(1, 0), b3, voffB);
;             PG8_BAR; PG8_WAIT_L(0); PG8_MMA(0, 1, At, B1); PG8_BAR;
;             PG8_LDA(At, 1, 1); PG8_STAGE(PG8_SA(1, 0), a3, voffA);
;             PG8_BAR; PG8_WAIT_L(0); PG8_MMA(1, 0, At, B0); PG8_BAR; PG8_SCHED;
;             PG8_STAGE(PG8_SB(1, 1), b3 + hstepB, voffB);
;             PG8_WAIT_V(6); PG8_BAR; PG8_MMA(1, 1, At, B1); PG8_BAR;
	s_add_i32 s62, 0, 0x18000
	v_add_u32_e32 v164, s62, v147
	ds_read_b128 v[152:155], v164
	ds_read_b128 v[156:159], v164 offset:1024
	ds_read_b128 v[160:163], v164 offset:2048
	ds_read_b128 v[164:167], v164 offset:3072
	s_add_u32 s26, s26, 0x80000
	s_addc_u32 s27, s27, 0
	s_mov_b32 m0, s47
	ds_read_b128 v[168:171], v150 offset:32768
	ds_read_b128 v[172:175], v150 offset:33792
	ds_read_b128 v[176:179], v150 offset:34816
	ds_read_b128 v[180:183], v150 offset:35840
	ds_read_b128 v[184:187], v150 offset:36864
	ds_read_b128 v[188:191], v150 offset:37888
	ds_read_b128 v[192:195], v150 offset:38912
	ds_read_b128 v[196:199], v150 offset:39936
	global_load_lds_dwordx4 v134, s[26:27]
	s_mov_b32 m0, s48
	s_nop 0
	global_load_lds_dwordx4 v132, s[26:27]
	s_add_i32 s63, 0, 0x1c000
	s_add_u32 s26, s24, 0x8000
	s_addc_u32 s27, s25, 0
	s_add_i32 s62, s62, s38
	v_add_u32_e32 v212, s63, v147
	s_mov_b32 m0, s62
	ds_read_b128 v[200:203], v212
	ds_read_b128 v[204:207], v212 offset:1024
	ds_read_b128 v[208:211], v212 offset:2048
	ds_read_b128 v[212:215], v212 offset:3072
	s_waitcnt vmcnt(8)
	s_waitcnt lgkmcnt(0)
	s_barrier
	v_mfma_f32_16x16x32_bf16 v[124:127], v[152:155], v[168:171], v[124:127]
	v_mfma_f32_16x16x32_bf16 v[120:123], v[160:163], v[168:171], v[120:123]
	v_mfma_f32_16x16x32_bf16 v[108:111], v[152:155], v[176:179], v[108:111]
	v_mfma_f32_16x16x32_bf16 v[104:107], v[160:163], v[176:179], v[104:107]
	v_mfma_f32_16x16x32_bf16 v[92:95], v[152:155], v[184:187], v[92:95]
	v_mfma_f32_16x16x32_bf16 v[88:91], v[160:163], v[184:187], v[88:91]
	v_mfma_f32_16x16x32_bf16 v[76:79], v[152:155], v[192:195], v[76:79]
	v_mfma_f32_16x16x32_bf16 v[72:75], v[160:163], v[192:195], v[72:75]
	v_mfma_f32_16x16x32_bf16 v[124:127], v[156:159], v[172:175], v[124:127]
	v_mfma_f32_16x16x32_bf16 v[120:123], v[164:167], v[172:175], v[120:123]
	v_mfma_f32_16x16x32_bf16 v[108:111], v[156:159], v[180:183], v[108:111]
	v_mfma_f32_16x16x32_bf16 v[104:107], v[164:167], v[180:183], v[104:107]
	v_mfma_f32_16x16x32_bf16 v[92:95], v[156:159], v[188:191], v[92:95]
	v_mfma_f32_16x16x32_bf16 v[88:91], v[164:167], v[188:191], v[88:91]
	v_mfma_f32_16x16x32_bf16 v[76:79], v[156:159], v[196:199], v[76:79]
	v_mfma_f32_16x16x32_bf16 v[72:75], v[164:167], v[196:199], v[72:75]
	v_mfma_f32_16x16x32_bf16 v[116:119], v[200:203], v[168:171], v[116:119]
	v_mfma_f32_16x16x32_bf16 v[112:115], v[208:211], v[168:171], v[112:115]
	v_mfma_f32_16x16x32_bf16 v[100:103], v[200:203], v[176:179], v[100:103]
	v_mfma_f32_16x16x32_bf16 v[96:99], v[208:211], v[176:179], v[96:99]
	v_mfma_f32_16x16x32_bf16 v[84:87], v[200:203], v[184:187], v[84:87]
	v_mfma_f32_16x16x32_bf16 v[80:83], v[208:211], v[184:187], v[80:83]
	v_mfma_f32_16x16x32_bf16 v[68:71], v[200:203], v[192:195], v[68:71]
	v_mfma_f32_16x16x32_bf16 v[64:67], v[208:211], v[192:195], v[64:67]
	v_mfma_f32_16x16x32_bf16 v[116:119], v[204:207], v[172:175], v[116:119]
	v_mfma_f32_16x16x32_bf16 v[112:115], v[212:215], v[172:175], v[112:115]
	v_mfma_f32_16x16x32_bf16 v[100:103], v[204:207], v[180:183], v[100:103]
	v_mfma_f32_16x16x32_bf16 v[96:99], v[212:215], v[180:183], v[96:99]
	v_mfma_f32_16x16x32_bf16 v[84:87], v[204:207], v[188:191], v[84:87]
	v_mfma_f32_16x16x32_bf16 v[80:83], v[212:215], v[188:191], v[80:83]
	v_mfma_f32_16x16x32_bf16 v[68:71], v[204:207], v[196:199], v[68:71]
	v_mfma_f32_16x16x32_bf16 v[64:67], v[212:215], v[196:199], v[64:67]
	s_barrier
	global_load_lds_dwordx4 v128, s[26:27]
	s_add_i32 m0, s62, 0x2000
	s_nop 0
	global_load_lds_dwordx4 v130, s[26:27]
	s_mov_b32 m0, s50
	v_lshl_add_u64 v[144:145], v[144:145], 0, s[10:11]
	ds_read_b128 v[168:171], v150 offset:49152
	ds_read_b128 v[172:175], v150 offset:50176
	ds_read_b128 v[176:179], v150 offset:51200
	ds_read_b128 v[180:183], v150 offset:52224
	ds_read_b128 v[184:187], v150 offset:53248
	ds_read_b128 v[188:191], v150 offset:54272
	ds_read_b128 v[192:195], v150 offset:55296
	ds_read_b128 v[196:199], v150 offset:56320
	global_load_lds_dwordx4 v[144:145], off
	v_lshl_add_u64 v[144:145], v[216:217], 0, s[10:11]
	s_mov_b32 m0, s51
	s_nop 0
	global_load_lds_dwordx4 v[144:145], off
	s_add_u32 s24, s24, 0xc000
	s_addc_u32 s25, s25, 0
	s_add_i32 s26, s63, s38
	s_mov_b32 m0, s26
	s_nop 0
	global_load_lds_dwordx4 v128, s[24:25]
	s_add_i32 m0, s26, 0x2000
	s_nop 0
	global_load_lds_dwordx4 v130, s[24:25]
	s_add_i32 s61, s61, 2
	s_add_u32 s59, s59, 0x10000
	s_addc_u32 s60, s60, 0
	s_add_u32 s22, s22, 0x100
	s_addc_u32 s23, s23, 0
	s_cmp_gt_u32 s61, 29
	s_waitcnt vmcnt(8)
	s_waitcnt lgkmcnt(0)
	s_barrier
	v_mfma_f32_16x16x32_bf16 v[60:63], v[152:155], v[168:171], v[60:63]
	v_mfma_f32_16x16x32_bf16 v[56:59], v[160:163], v[168:171], v[56:59]
	v_mfma_f32_16x16x32_bf16 v[44:47], v[152:155], v[176:179], v[44:47]
	v_mfma_f32_16x16x32_bf16 v[40:43], v[160:163], v[176:179], v[40:43]
	v_mfma_f32_16x16x32_bf16 v[28:31], v[152:155], v[184:187], v[28:31]
	v_mfma_f32_16x16x32_bf16 v[24:27], v[160:163], v[184:187], v[24:27]
	v_mfma_f32_16x16x32_bf16 v[12:15], v[152:155], v[192:195], v[12:15]
	v_mfma_f32_16x16x32_bf16 v[8:11], v[160:163], v[192:195], v[8:11]
	v_mfma_f32_16x16x32_bf16 v[60:63], v[156:159], v[172:175], v[60:63]
	v_mfma_f32_16x16x32_bf16 v[56:59], v[164:167], v[172:175], v[56:59]
	v_mfma_f32_16x16x32_bf16 v[44:47], v[156:159], v[180:183], v[44:47]
	v_mfma_f32_16x16x32_bf16 v[40:43], v[164:167], v[180:183], v[40:43]
	v_mfma_f32_16x16x32_bf16 v[28:31], v[156:159], v[188:191], v[28:31]
	v_mfma_f32_16x16x32_bf16 v[24:27], v[164:167], v[188:191], v[24:27]
	v_mfma_f32_16x16x32_bf16 v[12:15], v[156:159], v[196:199], v[12:15]
	v_mfma_f32_16x16x32_bf16 v[8:11], v[164:167], v[196:199], v[8:11]
	v_mfma_f32_16x16x32_bf16 v[52:55], v[200:203], v[168:171], v[52:55]
	v_mfma_f32_16x16x32_bf16 v[48:51], v[208:211], v[168:171], v[48:51]
	v_mfma_f32_16x16x32_bf16 v[36:39], v[200:203], v[176:179], v[36:39]
	v_mfma_f32_16x16x32_bf16 v[32:35], v[208:211], v[176:179], v[32:35]
	v_mfma_f32_16x16x32_bf16 v[20:23], v[200:203], v[184:187], v[20:23]
	v_mfma_f32_16x16x32_bf16 v[16:19], v[208:211], v[184:187], v[16:19]
	v_mfma_f32_16x16x32_bf16 v[4:7], v[200:203], v[192:195], v[4:7]
	v_mfma_f32_16x16x32_bf16 v[0:3], v[208:211], v[192:195], v[0:3]
	v_mfma_f32_16x16x32_bf16 v[52:55], v[204:207], v[172:175], v[52:55]
	v_mfma_f32_16x16x32_bf16 v[48:51], v[212:215], v[172:175], v[48:51]
	v_mfma_f32_16x16x32_bf16 v[36:39], v[204:207], v[180:183], v[36:39]
	v_mfma_f32_16x16x32_bf16 v[32:35], v[212:215], v[180:183], v[32:35]
	v_mfma_f32_16x16x32_bf16 v[20:23], v[204:207], v[188:191], v[20:23]
	v_mfma_f32_16x16x32_bf16 v[16:19], v[212:215], v[188:191], v[16:19]
	v_mfma_f32_16x16x32_bf16 v[4:7], v[204:207], v[196:199], v[4:7]
	v_mfma_f32_16x16x32_bf16 v[0:3], v[212:215], v[196:199], v[0:3]
	s_cbranch_scc1 .Lunit_exit_0
	s_barrier
	s_branch .LBB0_79

; #define PG8_STAGE(bufoff, gbase, voff) do { _Pragma("unroll") for (int _i = 0; _i < 2; ++_i) \
;         __builtin_amdgcn_global_load_lds((const unsigned*)((const char*)(gbase) + (voff)[_i]), (PG8_LAS unsigned*)(lds + (bufoff) + ldsw + _i * 8192), 16, 0, 0); } while (0)
; #define PG8_LDA(dst, b, h) do { _Pragma("unroll") for (int m = 0; m < 4; ++m) _Pragma("unroll") for (int k = 0; k < 2; ++k) dst[m][k] = *(const PG8_LAS bf16x8*)(lds + PG8_SA(b, h) + aoff + m * 2048 + k * 1024); } while (0)
; #define PG8_LDB(dst, b, h) do { _Pragma("unroll") for (int n = 0; n < 2; ++n) _Pragma("unroll") for (int k = 0; k < 2; ++k) dst[n][k] = *(const PG8_LAS bf16x8*)(lds + PG8_SB(b, h) + boff + n * 2048 + k * 1024); } while (0)
; #define PG8_MMA(ai, bj, At, Bt) do { __builtin_amdgcn_s_setprio(1); _Pragma("unroll") for (int m = 0; m < 4; ++m) _Pragma("unroll") for (int n = 0; n < 2; ++n) _Pragma("unroll") for (int k = 0; k < 2; ++k) \
;         acc[ai][bj][m][n] = __builtin_amdgcn_mfma_f32_16x16x32_bf16(Bt[n][k], At[m][k], acc[ai][bj][m][n], 0, 0, 0); __builtin_amdgcn_s_setprio(0); } while (0)
; #define PG8_WAIT_L(n) asm volatile("s_waitcnt lgkmcnt(" #n ")" ::: "memory")
; #define PG8_BAR __builtin_amdgcn_s_barrier()
; #define PG8_SCHED __builtin_amdgcn_sched_barrier(0)
; template <class Epi, class Sched>
; __device__ __forceinline__ void gemm_phase(PG8_LAS unsigned char* lds, const Gemm g, const Sched& S, const Epi& E) {
;     ...
;         for (int t = 0; t < nt; t += 2) {
;             const bool last = (t == nt - 2);
;             const char* a1 = cA + (size_t)(t + 1) * kstep;
;             const char* a2 = last ? nA : cA + (size_t)(t + 2) * kstep; const char* b2 = last ? nB : cB + (size_t)(t + 2) * kstepB;
;             const char* a3 = a2 + kstep; const char* b3 = b2 + kstepB;
;             if (last && has_next) S.a_ready(nxt);
;             PG8_LDB(B0, 0, 0); PG8_SCHED; PG8_LDA(At, 0, 0); PG8_STAGE(PG8_SA(1, 1), a1 + hstep, voffA);
;             PG8_WAIT_L(8); PG8_BAR; PG8_WAIT_L(0); PG8_MMA(0, 0, At, B0); PG8_BAR; PG8_SCHED;
;             PG8_LDB(B1, 0, 1); PG8_STAGE(PG8_SB(0, 0), b2, voffB);
;             PG8_BAR; PG8_WAIT_L(0); PG8_MMA(0, 1, At, B1); PG8_BAR;
;             PG8_LDA(At, 0, 1); PG8_STAGE(PG8_SA(0, 0), a2, voffA);
;             PG8_BAR; PG8_WAIT_L(0); PG8_MMA(1, 0, At, B0); PG8_BAR; PG8_SCHED;
;             PG8_STAGE(PG8_SB(0, 1), b2 + hstepB, voffB);
.Lhalf_skip_y_1:
.LBB0_155:
	ds_read_b128 v[144:147], v153
	ds_read_b128 v[156:159], v153 offset:1024
	ds_read_b128 v[160:163], v153 offset:2048
	ds_read_b128 v[164:167], v153 offset:3072
	s_add_u32 s26, s24, 0x100
	s_addc_u32 s27, s25, 0
	s_cmpk_eq_i32 s67, 0x52
	s_cselect_b32 s31, s7, s27
	s_cselect_b32 s30, s6, s26
	s_cselect_b32 s29, s9, s66
	s_cselect_b32 s28, s8, s65
	v_lshl_add_u64 v[148:149], s[24:25], 0, v[136:137]
	s_add_i32 m0, s51, 0xc000
	ds_read_b128 v[168:171], v154
	ds_read_b128 v[172:175], v154 offset:1024
	ds_read_b128 v[176:179], v154 offset:2048
	ds_read_b128 v[180:183], v154 offset:3072
	ds_read_b128 v[184:187], v154 offset:4096
	ds_read_b128 v[188:191], v154 offset:5120
	ds_read_b128 v[192:195], v154 offset:6144
	ds_read_b128 v[196:199], v154 offset:7168
	global_load_lds_dwordx4 v[148:149], off
	v_lshl_add_u64 v[148:149], s[24:25], 0, v[138:139]
	s_add_i32 m0, s51, 0xe000
	s_nop 0
	global_load_lds_dwordx4 v[148:149], off
	s_add_i32 s24, s59, s50
	s_mov_b32 m0, s24
	ds_read_b128 v[200:203], v155
	ds_read_b128 v[204:207], v155 offset:1024
	ds_read_b128 v[208:211], v155 offset:2048
	ds_read_b128 v[212:215], v155 offset:3072
	s_waitcnt vmcnt(8)
	s_waitcnt lgkmcnt(0)
	s_barrier
	v_mfma_f32_16x16x32_bf16 v[124:127], v[144:147], v[168:171], v[124:127]
	v_mfma_f32_16x16x32_bf16 v[120:123], v[160:163], v[168:171], v[120:123]
	v_mfma_f32_16x16x32_bf16 v[108:111], v[144:147], v[176:179], v[108:111]
	v_mfma_f32_16x16x32_bf16 v[104:107], v[160:163], v[176:179], v[104:107]
	v_mfma_f32_16x16x32_bf16 v[92:95], v[144:147], v[184:187], v[92:95]
	v_mfma_f32_16x16x32_bf16 v[88:91], v[160:163], v[184:187], v[88:91]
	v_mfma_f32_16x16x32_bf16 v[76:79], v[144:147], v[192:195], v[76:79]
	v_mfma_f32_16x16x32_bf16 v[72:75], v[160:163], v[192:195], v[72:75]
	v_mfma_f32_16x16x32_bf16 v[124:127], v[156:159], v[172:175], v[124:127]
	v_mfma_f32_16x16x32_bf16 v[120:123], v[164:167], v[172:175], v[120:123]
	v_mfma_f32_16x16x32_bf16 v[108:111], v[156:159], v[180:183], v[108:111]
	v_mfma_f32_16x16x32_bf16 v[104:107], v[164:167], v[180:183], v[104:107]
	v_mfma_f32_16x16x32_bf16 v[92:95], v[156:159], v[188:191], v[92:95]
	v_mfma_f32_16x16x32_bf16 v[88:91], v[164:167], v[188:191], v[88:91]
	v_mfma_f32_16x16x32_bf16 v[76:79], v[156:159], v[196:199], v[76:79]
	v_mfma_f32_16x16x32_bf16 v[72:75], v[164:167], v[196:199], v[72:75]
	v_mfma_f32_16x16x32_bf16 v[116:119], v[200:203], v[168:171], v[116:119]
	v_mfma_f32_16x16x32_bf16 v[112:115], v[208:211], v[168:171], v[112:115]
	v_mfma_f32_16x16x32_bf16 v[100:103], v[200:203], v[176:179], v[100:103]
	v_mfma_f32_16x16x32_bf16 v[96:99], v[208:211], v[176:179], v[96:99]
	v_mfma_f32_16x16x32_bf16 v[84:87], v[200:203], v[184:187], v[84:87]
	v_mfma_f32_16x16x32_bf16 v[80:83], v[208:211], v[184:187], v[80:83]
	v_mfma_f32_16x16x32_bf16 v[68:71], v[200:203], v[192:195], v[68:71]
	v_mfma_f32_16x16x32_bf16 v[64:67], v[208:211], v[192:195], v[64:67]
	v_mfma_f32_16x16x32_bf16 v[116:119], v[204:207], v[172:175], v[116:119]
	v_mfma_f32_16x16x32_bf16 v[112:115], v[212:215], v[172:175], v[112:115]
	v_mfma_f32_16x16x32_bf16 v[100:103], v[204:207], v[180:183], v[100:103]
	v_mfma_f32_16x16x32_bf16 v[96:99], v[212:215], v[180:183], v[96:99]
	v_mfma_f32_16x16x32_bf16 v[84:87], v[204:207], v[188:191], v[84:87]
	v_mfma_f32_16x16x32_bf16 v[80:83], v[212:215], v[188:191], v[80:83]
	v_mfma_f32_16x16x32_bf16 v[68:71], v[204:207], v[196:199], v[68:71]
	v_mfma_f32_16x16x32_bf16 v[64:67], v[212:215], v[196:199], v[64:67]
	s_barrier
	global_load_lds_dwordx4 v128, s[28:29]
	s_add_i32 m0, s24, 0x2000
	s_nop 0
	global_load_lds_dwordx4 v132, s[28:29]
	s_mov_b32 m0, s51
	v_lshl_add_u64 v[148:149], s[30:31], 0, v[130:131]
	ds_read_b128 v[168:171], v154 offset:16384
	ds_read_b128 v[172:175], v154 offset:17408
	ds_read_b128 v[176:179], v154 offset:18432
	ds_read_b128 v[180:183], v154 offset:19456
	ds_read_b128 v[184:187], v154 offset:20480
	ds_read_b128 v[188:191], v154 offset:21504
	ds_read_b128 v[192:195], v154 offset:22528
	ds_read_b128 v[196:199], v154 offset:23552
	global_load_lds_dwordx4 v[148:149], off
	v_lshl_add_u64 v[216:217], s[30:31], 0, v[134:135]
	s_mov_b32 m0, s52
	s_nop 0
	global_load_lds_dwordx4 v[216:217], off
	s_add_u32 s24, s28, 0x4000
	s_addc_u32 s25, s29, 0
	s_add_i32 s68, s60, s50
	s_mov_b32 m0, s68
	s_nop 0
	global_load_lds_dwordx4 v128, s[24:25]
	s_add_i32 m0, s68, 0x2000
	s_nop 0
	global_load_lds_dwordx4 v132, s[24:25]
	s_waitcnt vmcnt(8)
	s_waitcnt lgkmcnt(0)
	s_barrier
	v_mfma_f32_16x16x32_bf16 v[60:63], v[144:147], v[168:171], v[60:63]
	v_mfma_f32_16x16x32_bf16 v[56:59], v[160:163], v[168:171], v[56:59]
	v_mfma_f32_16x16x32_bf16 v[44:47], v[144:147], v[176:179], v[44:47]
	v_mfma_f32_16x16x32_bf16 v[40:43], v[160:163], v[176:179], v[40:43]
	v_mfma_f32_16x16x32_bf16 v[28:31], v[144:147], v[184:187], v[28:31]
	v_mfma_f32_16x16x32_bf16 v[24:27], v[160:163], v[184:187], v[24:27]
	v_mfma_f32_16x16x32_bf16 v[12:15], v[144:147], v[192:195], v[12:15]
	v_mfma_f32_16x16x32_bf16 v[8:11], v[160:163], v[192:195], v[8:11]
	v_mfma_f32_16x16x32_bf16 v[60:63], v[156:159], v[172:175], v[60:63]
	v_mfma_f32_16x16x32_bf16 v[56:59], v[164:167], v[172:175], v[56:59]
	v_mfma_f32_16x16x32_bf16 v[44:47], v[156:159], v[180:183], v[44:47]
	v_mfma_f32_16x16x32_bf16 v[40:43], v[164:167], v[180:183], v[40:43]
	v_mfma_f32_16x16x32_bf16 v[28:31], v[156:159], v[188:191], v[28:31]
	v_mfma_f32_16x16x32_bf16 v[24:27], v[164:167], v[188:191], v[24:27]
	v_mfma_f32_16x16x32_bf16 v[12:15], v[156:159], v[196:199], v[12:15]
	v_mfma_f32_16x16x32_bf16 v[8:11], v[164:167], v[196:199], v[8:11]
	v_mfma_f32_16x16x32_bf16 v[52:55], v[200:203], v[168:171], v[52:55]
	v_mfma_f32_16x16x32_bf16 v[48:51], v[208:211], v[168:171], v[48:51]
	v_mfma_f32_16x16x32_bf16 v[36:39], v[200:203], v[176:179], v[36:39]
	v_mfma_f32_16x16x32_bf16 v[32:35], v[208:211], v[176:179], v[32:35]
	v_mfma_f32_16x16x32_bf16 v[20:23], v[200:203], v[184:187], v[20:23]
	v_mfma_f32_16x16x32_bf16 v[16:19], v[208:211], v[184:187], v[16:19]
	v_mfma_f32_16x16x32_bf16 v[4:7], v[200:203], v[192:195], v[4:7]
	v_mfma_f32_16x16x32_bf16 v[0:3], v[208:211], v[192:195], v[0:3]
	v_mfma_f32_16x16x32_bf16 v[52:55], v[204:207], v[172:175], v[52:55]
	v_mfma_f32_16x16x32_bf16 v[48:51], v[212:215], v[172:175], v[48:51]
	v_mfma_f32_16x16x32_bf16 v[36:39], v[204:207], v[180:183], v[36:39]
	v_mfma_f32_16x16x32_bf16 v[32:35], v[212:215], v[180:183], v[32:35]
	v_mfma_f32_16x16x32_bf16 v[20:23], v[204:207], v[188:191], v[20:23]
	v_mfma_f32_16x16x32_bf16 v[16:19], v[212:215], v[188:191], v[16:19]
	v_mfma_f32_16x16x32_bf16 v[4:7], v[204:207], v[196:199], v[4:7]
	v_mfma_f32_16x16x32_bf16 v[0:3], v[212:215], v[196:199], v[0:3]
	s_barrier
; #define PG8_STAGE(bufoff, gbase, voff) do { _Pragma("unroll") for (int _i = 0; _i < 2; ++_i) \
;         __builtin_amdgcn_global_load_lds((const unsigned*)((const char*)(gbase) + (voff)[_i]), (PG8_LAS unsigned*)(lds + (bufoff) + ldsw + _i * 8192), 16, 0, 0); } while (0)
; #define PG8_LDA(dst, b, h) do { _Pragma("unroll") for (int m = 0; m < 4; ++m) _Pragma("unroll") for (int k = 0; k < 2; ++k) dst[m][k] = *(const PG8_LAS bf16x8*)(lds + PG8_SA(b, h) + aoff + m * 2048 + k * 1024); } while (0)
; #define PG8_LDB(dst, b, h) do { _Pragma("unroll") for (int n = 0; n < 2; ++n) _Pragma("unroll") for (int k = 0; k < 2; ++k) dst[n][k] = *(const PG8_LAS bf16x8*)(lds + PG8_SB(b, h) + boff + n * 2048 + k * 1024); } while (0)
; #define PG8_MMA(ai, bj, At, Bt) do { __builtin_amdgcn_s_setprio(1); _Pragma("unroll") for (int m = 0; m < 4; ++m) _Pragma("unroll") for (int n = 0; n < 2; ++n) _Pragma("unroll") for (int k = 0; k < 2; ++k) \
;         acc[ai][bj][m][n] = __builtin_amdgcn_mfma_f32_16x16x32_bf16(Bt[n][k], At[m][k], acc[ai][bj][m][n], 0, 0, 0); __builtin_amdgcn_s_setprio(0); } while (0)
; #define PG8_WAIT_V(n) asm volatile("s_waitcnt vmcnt(" #n ")" ::: "memory")
; #define PG8_WAIT_L(n) asm volatile("s_waitcnt lgkmcnt(" #n ")" ::: "memory")
; #define PG8_BAR __builtin_amdgcn_s_barrier()
; #define PG8_SCHED __builtin_amdgcn_sched_barrier(0)
; template <class Epi, class Sched>
; __device__ __forceinline__ void gemm_phase(PG8_LAS unsigned char* lds, const Gemm g, const Sched& S, const Epi& E) {
;     ...
;             PG8_WAIT_V(6); PG8_BAR; PG8_MMA(1, 1, At, B1); PG8_BAR;
;             PG8_LDB(B0, 1, 0); PG8_SCHED; PG8_LDA(At, 1, 0); PG8_STAGE(PG8_SA(0, 1), a2 + hstep, voffA);
;             PG8_WAIT_L(8); PG8_BAR; PG8_WAIT_L(0); PG8_MMA(0, 0, At, B0); PG8_BAR; PG8_SCHED;
;             PG8_LDB(B1, 1, 1); PG8_STAGE(PG8_SB(1, 0), b3, voffB);
;             PG8_BAR; PG8_WAIT_L(0); PG8_MMA(0, 1, At, B1); PG8_BAR;
;             PG8_LDA(At, 1, 1); PG8_STAGE(PG8_SA(1, 0), a3, voffA);
;             PG8_BAR; PG8_WAIT_L(0); PG8_MMA(1, 0, At, B0); PG8_BAR; PG8_SCHED;
;             PG8_STAGE(PG8_SB(1, 1), b3 + hstepB, voffB);
;             PG8_WAIT_V(6); PG8_BAR; PG8_MMA(1, 1, At, B1); PG8_BAR;
	s_add_i32 s68, 0, 0x18000
	v_add_u32_e32 v164, s68, v151
	ds_read_b128 v[144:147], v164
	ds_read_b128 v[156:159], v164 offset:1024
	ds_read_b128 v[160:163], v164 offset:2048
	ds_read_b128 v[164:167], v164 offset:3072
	s_add_u32 s24, s30, 0x158000
	s_addc_u32 s25, s31, 0
	s_mov_b32 m0, s53
	ds_read_b128 v[168:171], v154 offset:32768
	ds_read_b128 v[172:175], v154 offset:33792
	ds_read_b128 v[176:179], v154 offset:34816
	ds_read_b128 v[180:183], v154 offset:35840
	ds_read_b128 v[184:187], v154 offset:36864
	ds_read_b128 v[188:191], v154 offset:37888
	ds_read_b128 v[192:195], v154 offset:38912
	ds_read_b128 v[196:199], v154 offset:39936
	global_load_lds_dwordx4 v130, s[24:25]
	s_mov_b32 m0, s54
	s_nop 0
	global_load_lds_dwordx4 v134, s[24:25]
	s_add_i32 s30, 0, 0x1c000
	s_add_u32 s24, s28, 0x8000
	s_addc_u32 s25, s29, 0
	s_add_i32 s31, s68, s50
	v_add_u32_e32 v212, s30, v151
	s_mov_b32 m0, s31
	ds_read_b128 v[200:203], v212
	ds_read_b128 v[204:207], v212 offset:1024
	ds_read_b128 v[208:211], v212 offset:2048
	ds_read_b128 v[212:215], v212 offset:3072
	s_waitcnt vmcnt(8)
	s_waitcnt lgkmcnt(0)
	s_barrier
	v_mfma_f32_16x16x32_bf16 v[124:127], v[144:147], v[168:171], v[124:127]
	v_mfma_f32_16x16x32_bf16 v[120:123], v[160:163], v[168:171], v[120:123]
	v_mfma_f32_16x16x32_bf16 v[108:111], v[144:147], v[176:179], v[108:111]
	v_mfma_f32_16x16x32_bf16 v[104:107], v[160:163], v[176:179], v[104:107]
	v_mfma_f32_16x16x32_bf16 v[92:95], v[144:147], v[184:187], v[92:95]
	v_mfma_f32_16x16x32_bf16 v[88:91], v[160:163], v[184:187], v[88:91]
	v_mfma_f32_16x16x32_bf16 v[76:79], v[144:147], v[192:195], v[76:79]
	v_mfma_f32_16x16x32_bf16 v[72:75], v[160:163], v[192:195], v[72:75]
	v_mfma_f32_16x16x32_bf16 v[124:127], v[156:159], v[172:175], v[124:127]
	v_mfma_f32_16x16x32_bf16 v[120:123], v[164:167], v[172:175], v[120:123]
	v_mfma_f32_16x16x32_bf16 v[108:111], v[156:159], v[180:183], v[108:111]
	v_mfma_f32_16x16x32_bf16 v[104:107], v[164:167], v[180:183], v[104:107]
	v_mfma_f32_16x16x32_bf16 v[92:95], v[156:159], v[188:191], v[92:95]
	v_mfma_f32_16x16x32_bf16 v[88:91], v[164:167], v[188:191], v[88:91]
	v_mfma_f32_16x16x32_bf16 v[76:79], v[156:159], v[196:199], v[76:79]
	v_mfma_f32_16x16x32_bf16 v[72:75], v[164:167], v[196:199], v[72:75]
	v_mfma_f32_16x16x32_bf16 v[116:119], v[200:203], v[168:171], v[116:119]
	v_mfma_f32_16x16x32_bf16 v[112:115], v[208:211], v[168:171], v[112:115]
	v_mfma_f32_16x16x32_bf16 v[100:103], v[200:203], v[176:179], v[100:103]
	v_mfma_f32_16x16x32_bf16 v[96:99], v[208:211], v[176:179], v[96:99]
	v_mfma_f32_16x16x32_bf16 v[84:87], v[200:203], v[184:187], v[84:87]
	v_mfma_f32_16x16x32_bf16 v[80:83], v[208:211], v[184:187], v[80:83]
	v_mfma_f32_16x16x32_bf16 v[68:71], v[200:203], v[192:195], v[68:71]
	v_mfma_f32_16x16x32_bf16 v[64:67], v[208:211], v[192:195], v[64:67]
	v_mfma_f32_16x16x32_bf16 v[116:119], v[204:207], v[172:175], v[116:119]
	v_mfma_f32_16x16x32_bf16 v[112:115], v[212:215], v[172:175], v[112:115]
	v_mfma_f32_16x16x32_bf16 v[100:103], v[204:207], v[180:183], v[100:103]
	v_mfma_f32_16x16x32_bf16 v[96:99], v[212:215], v[180:183], v[96:99]
	v_mfma_f32_16x16x32_bf16 v[84:87], v[204:207], v[188:191], v[84:87]
	v_mfma_f32_16x16x32_bf16 v[80:83], v[212:215], v[188:191], v[80:83]
	v_mfma_f32_16x16x32_bf16 v[68:71], v[204:207], v[196:199], v[68:71]
	v_mfma_f32_16x16x32_bf16 v[64:67], v[212:215], v[196:199], v[64:67]
	s_barrier
	global_load_lds_dwordx4 v128, s[24:25]
	s_add_i32 m0, s31, 0x2000
	s_nop 0
	global_load_lds_dwordx4 v132, s[24:25]
	s_mov_b32 m0, s56
	v_lshl_add_u64 v[148:149], v[148:149], 0, s[14:15]
	ds_read_b128 v[168:171], v154 offset:49152
	ds_read_b128 v[172:175], v154 offset:50176
	ds_read_b128 v[176:179], v154 offset:51200
	ds_read_b128 v[180:183], v154 offset:52224
	ds_read_b128 v[184:187], v154 offset:53248
	ds_read_b128 v[188:191], v154 offset:54272
	ds_read_b128 v[192:195], v154 offset:55296
	ds_read_b128 v[196:199], v154 offset:56320
	global_load_lds_dwordx4 v[148:149], off
	v_lshl_add_u64 v[148:149], v[216:217], 0, s[14:15]
	s_mov_b32 m0, s57
	s_nop 0
	global_load_lds_dwordx4 v[148:149], off
	s_add_u32 s24, s28, 0xc000
	s_addc_u32 s25, s29, 0
	s_add_i32 s28, s30, s50
	s_mov_b32 m0, s28
	s_nop 0
	global_load_lds_dwordx4 v128, s[24:25]
	s_add_i32 m0, s28, 0x2000
	s_nop 0
	global_load_lds_dwordx4 v132, s[24:25]
	s_add_i32 s67, s67, 2
	s_add_u32 s65, s65, 0x10000
	s_addc_u32 s66, s66, 0
	s_cmpk_gt_u32 s67, 0x53
	s_mov_b64 s[24:25], s[26:27]
	s_waitcnt vmcnt(8)
	s_waitcnt lgkmcnt(0)
	s_barrier
	v_mfma_f32_16x16x32_bf16 v[60:63], v[144:147], v[168:171], v[60:63]
	v_mfma_f32_16x16x32_bf16 v[56:59], v[160:163], v[168:171], v[56:59]
	v_mfma_f32_16x16x32_bf16 v[44:47], v[144:147], v[176:179], v[44:47]
	v_mfma_f32_16x16x32_bf16 v[40:43], v[160:163], v[176:179], v[40:43]
	v_mfma_f32_16x16x32_bf16 v[28:31], v[144:147], v[184:187], v[28:31]
	v_mfma_f32_16x16x32_bf16 v[24:27], v[160:163], v[184:187], v[24:27]
	v_mfma_f32_16x16x32_bf16 v[12:15], v[144:147], v[192:195], v[12:15]
	v_mfma_f32_16x16x32_bf16 v[8:11], v[160:163], v[192:195], v[8:11]
	v_mfma_f32_16x16x32_bf16 v[60:63], v[156:159], v[172:175], v[60:63]
	v_mfma_f32_16x16x32_bf16 v[56:59], v[164:167], v[172:175], v[56:59]
	v_mfma_f32_16x16x32_bf16 v[44:47], v[156:159], v[180:183], v[44:47]
	v_mfma_f32_16x16x32_bf16 v[40:43], v[164:167], v[180:183], v[40:43]
	v_mfma_f32_16x16x32_bf16 v[28:31], v[156:159], v[188:191], v[28:31]
	v_mfma_f32_16x16x32_bf16 v[24:27], v[164:167], v[188:191], v[24:27]
	v_mfma_f32_16x16x32_bf16 v[12:15], v[156:159], v[196:199], v[12:15]
	v_mfma_f32_16x16x32_bf16 v[8:11], v[164:167], v[196:199], v[8:11]
	v_mfma_f32_16x16x32_bf16 v[52:55], v[200:203], v[168:171], v[52:55]
	v_mfma_f32_16x16x32_bf16 v[48:51], v[208:211], v[168:171], v[48:51]
	v_mfma_f32_16x16x32_bf16 v[36:39], v[200:203], v[176:179], v[36:39]
	v_mfma_f32_16x16x32_bf16 v[32:35], v[208:211], v[176:179], v[32:35]
	v_mfma_f32_16x16x32_bf16 v[20:23], v[200:203], v[184:187], v[20:23]
	v_mfma_f32_16x16x32_bf16 v[16:19], v[208:211], v[184:187], v[16:19]
	v_mfma_f32_16x16x32_bf16 v[4:7], v[200:203], v[192:195], v[4:7]
	v_mfma_f32_16x16x32_bf16 v[0:3], v[208:211], v[192:195], v[0:3]
	v_mfma_f32_16x16x32_bf16 v[52:55], v[204:207], v[172:175], v[52:55]
	v_mfma_f32_16x16x32_bf16 v[48:51], v[212:215], v[172:175], v[48:51]
	v_mfma_f32_16x16x32_bf16 v[36:39], v[204:207], v[180:183], v[36:39]
	v_mfma_f32_16x16x32_bf16 v[32:35], v[212:215], v[180:183], v[32:35]
	v_mfma_f32_16x16x32_bf16 v[20:23], v[204:207], v[188:191], v[20:23]
	v_mfma_f32_16x16x32_bf16 v[16:19], v[212:215], v[188:191], v[16:19]
	v_mfma_f32_16x16x32_bf16 v[4:7], v[204:207], v[196:199], v[4:7]
	v_mfma_f32_16x16x32_bf16 v[0:3], v[212:215], v[196:199], v[0:3]
	s_cbranch_scc1 .Lunit_exit_1
	s_barrier
	s_branch .LBB0_155

; #define PG8_STAGE(bufoff, gbase, voff) do { _Pragma("unroll") for (int _i = 0; _i < 2; ++_i) \
;         __builtin_amdgcn_global_load_lds((const unsigned*)((const char*)(gbase) + (voff)[_i]), (PG8_LAS unsigned*)(lds + (bufoff) + ldsw + _i * 8192), 16, 0, 0); } while (0)
; #define PG8_LDA(dst, b, h) do { _Pragma("unroll") for (int m = 0; m < 4; ++m) _Pragma("unroll") for (int k = 0; k < 2; ++k) dst[m][k] = *(const PG8_LAS bf16x8*)(lds + PG8_SA(b, h) + aoff + m * 2048 + k * 1024); } while (0)
; #define PG8_LDB(dst, b, h) do { _Pragma("unroll") for (int n = 0; n < 2; ++n) _Pragma("unroll") for (int k = 0; k < 2; ++k) dst[n][k] = *(const PG8_LAS bf16x8*)(lds + PG8_SB(b, h) + boff + n * 2048 + k * 1024); } while (0)
; #define PG8_MMA(ai, bj, At, Bt) do { __builtin_amdgcn_s_setprio(1); _Pragma("unroll") for (int m = 0; m < 4; ++m) _Pragma("unroll") for (int n = 0; n < 2; ++n) _Pragma("unroll") for (int k = 0; k < 2; ++k) \
;         acc[ai][bj][m][n] = __builtin_amdgcn_mfma_f32_16x16x32_bf16(Bt[n][k], At[m][k], acc[ai][bj][m][n], 0, 0, 0); __builtin_amdgcn_s_setprio(0); } while (0)
; #define PG8_WAIT_V(n) asm volatile("s_waitcnt vmcnt(" #n ")" ::: "memory")
; template <class Epi, class Sched>
; __device__ __forceinline__ void gemm_phase(PG8_LAS unsigned char* lds, const Gemm g, const Sched& S, const Epi& E) {
;     ...
;         for (int t = 0; t < nt; t += 2) {
;             const bool last = (t == nt - 2);
;             const char* a1 = cA + (size_t)(t + 1) * kstep;
;             const char* a2 = last ? nA : cA + (size_t)(t + 2) * kstep; const char* b2 = last ? nB : cB + (size_t)(t + 2) * kstepB;
;             const char* a3 = a2 + kstep; const char* b3 = b2 + kstepB;
;             if (last && has_next) S.a_ready(nxt);
;             PG8_LDB(B0, 0, 0); PG8_SCHED; PG8_LDA(At, 0, 0); PG8_STAGE(PG8_SA(1, 1), a1 + hstep, voffA);
;             PG8_WAIT_L(8); PG8_BAR; PG8_WAIT_L(0); PG8_MMA(0, 0, At, B0); PG8_BAR; PG8_SCHED;
;             PG8_LDB(B1, 0, 1); PG8_STAGE(PG8_SB(0, 0), b2, voffB);
;             PG8_BAR; PG8_WAIT_L(0); PG8_MMA(0, 1, At, B1); PG8_BAR;
;             PG8_LDA(At, 0, 1); PG8_STAGE(PG8_SA(0, 0), a2, voffA);
;             PG8_BAR; PG8_WAIT_L(0); PG8_MMA(1, 0, At, B0); PG8_BAR; PG8_SCHED;
;             PG8_STAGE(PG8_SB(0, 1), b2 + hstepB, voffB);
;             PG8_WAIT_V(6); PG8_BAR; PG8_MMA(1, 1, At, B1); PG8_BAR;
.Lhalf_skip_y_2:
.LBB0_280:
	ds_read_b128 v[150:153], v147
	ds_read_b128 v[154:157], v147 offset:1024
	ds_read_b128 v[158:161], v147 offset:2048
	ds_read_b128 v[162:165], v147 offset:3072
	s_add_u32 s48, s6, 0xfff80080
	s_addc_u32 s49, s7, -1
	s_cmp_eq_u32 s69, 28
	s_cselect_b32 s51, s9, s49
	s_cselect_b32 s50, s29, s48
	s_cselect_b32 s49, s31, s68
	s_cselect_b32 s48, s47, s67
	s_add_i32 m0, s54, 0xc000
	ds_read_b128 v[166:169], v148
	ds_read_b128 v[170:173], v148 offset:1024
	ds_read_b128 v[174:177], v148 offset:2048
	ds_read_b128 v[178:181], v148 offset:3072
	ds_read_b128 v[182:185], v148 offset:4096
	ds_read_b128 v[186:189], v148 offset:5120
	ds_read_b128 v[190:193], v148 offset:6144
	ds_read_b128 v[194:197], v148 offset:7168
	global_load_lds_dwordx4 v136, s[6:7]
	s_add_i32 m0, s54, 0xe000
	s_nop 0
	global_load_lds_dwordx4 v138, s[6:7]
	s_add_i32 s70, s63, s53
	s_mov_b32 m0, s70
	ds_read_b128 v[198:201], v149
	ds_read_b128 v[202:205], v149 offset:1024
	ds_read_b128 v[206:209], v149 offset:2048
	ds_read_b128 v[210:213], v149 offset:3072
	s_waitcnt vmcnt(8)
	s_waitcnt lgkmcnt(0)
	s_barrier
	v_mfma_f32_16x16x32_bf16 v[124:127], v[150:153], v[166:169], v[124:127]
	v_mfma_f32_16x16x32_bf16 v[120:123], v[158:161], v[166:169], v[120:123]
	v_mfma_f32_16x16x32_bf16 v[108:111], v[150:153], v[174:177], v[108:111]
	v_mfma_f32_16x16x32_bf16 v[104:107], v[158:161], v[174:177], v[104:107]
	v_mfma_f32_16x16x32_bf16 v[92:95], v[150:153], v[182:185], v[92:95]
	v_mfma_f32_16x16x32_bf16 v[88:91], v[158:161], v[182:185], v[88:91]
	v_mfma_f32_16x16x32_bf16 v[76:79], v[150:153], v[190:193], v[76:79]
	v_mfma_f32_16x16x32_bf16 v[72:75], v[158:161], v[190:193], v[72:75]
	v_mfma_f32_16x16x32_bf16 v[124:127], v[154:157], v[170:173], v[124:127]
	v_mfma_f32_16x16x32_bf16 v[120:123], v[162:165], v[170:173], v[120:123]
	v_mfma_f32_16x16x32_bf16 v[108:111], v[154:157], v[178:181], v[108:111]
	v_mfma_f32_16x16x32_bf16 v[104:107], v[162:165], v[178:181], v[104:107]
	v_mfma_f32_16x16x32_bf16 v[92:95], v[154:157], v[186:189], v[92:95]
	v_mfma_f32_16x16x32_bf16 v[88:91], v[162:165], v[186:189], v[88:91]
	v_mfma_f32_16x16x32_bf16 v[76:79], v[154:157], v[194:197], v[76:79]
	v_mfma_f32_16x16x32_bf16 v[72:75], v[162:165], v[194:197], v[72:75]
	v_mfma_f32_16x16x32_bf16 v[116:119], v[198:201], v[166:169], v[116:119]
	v_mfma_f32_16x16x32_bf16 v[112:115], v[206:209], v[166:169], v[112:115]
	v_mfma_f32_16x16x32_bf16 v[100:103], v[198:201], v[174:177], v[100:103]
	v_mfma_f32_16x16x32_bf16 v[96:99], v[206:209], v[174:177], v[96:99]
	v_mfma_f32_16x16x32_bf16 v[84:87], v[198:201], v[182:185], v[84:87]
	v_mfma_f32_16x16x32_bf16 v[80:83], v[206:209], v[182:185], v[80:83]
	v_mfma_f32_16x16x32_bf16 v[68:71], v[198:201], v[190:193], v[68:71]
	v_mfma_f32_16x16x32_bf16 v[64:67], v[206:209], v[190:193], v[64:67]
	v_mfma_f32_16x16x32_bf16 v[116:119], v[202:205], v[170:173], v[116:119]
	v_mfma_f32_16x16x32_bf16 v[112:115], v[210:213], v[170:173], v[112:115]
	v_mfma_f32_16x16x32_bf16 v[100:103], v[202:205], v[178:181], v[100:103]
	v_mfma_f32_16x16x32_bf16 v[96:99], v[210:213], v[178:181], v[96:99]
	v_mfma_f32_16x16x32_bf16 v[84:87], v[202:205], v[186:189], v[84:87]
	v_mfma_f32_16x16x32_bf16 v[80:83], v[210:213], v[186:189], v[80:83]
	v_mfma_f32_16x16x32_bf16 v[68:71], v[202:205], v[194:197], v[68:71]
	v_mfma_f32_16x16x32_bf16 v[64:67], v[210:213], v[194:197], v[64:67]
	s_barrier
	global_load_lds_dwordx4 v128, s[48:49]
	s_add_i32 m0, s70, 0x2000
	s_nop 0
	global_load_lds_dwordx4 v132, s[48:49]
	s_mov_b32 m0, s54
	v_lshl_add_u64 v[214:215], s[50:51], 0, v[130:131]
	ds_read_b128 v[166:169], v148 offset:16384
	ds_read_b128 v[170:173], v148 offset:17408
	ds_read_b128 v[174:177], v148 offset:18432
	ds_read_b128 v[178:181], v148 offset:19456
	ds_read_b128 v[182:185], v148 offset:20480
	ds_read_b128 v[186:189], v148 offset:21504
	ds_read_b128 v[190:193], v148 offset:22528
	ds_read_b128 v[194:197], v148 offset:23552
	global_load_lds_dwordx4 v[214:215], off
	v_lshl_add_u64 v[216:217], s[50:51], 0, v[134:135]
	s_mov_b32 m0, s55
	s_nop 0
	global_load_lds_dwordx4 v[216:217], off
	s_add_u32 s70, s48, 0x4000
	s_addc_u32 s71, s49, 0
	s_add_i32 s72, s64, s53
	s_mov_b32 m0, s72
	s_nop 0
	global_load_lds_dwordx4 v128, s[70:71]
	s_add_i32 m0, s72, 0x2000
	s_nop 0
	global_load_lds_dwordx4 v132, s[70:71]
	s_waitcnt vmcnt(8)
	s_waitcnt lgkmcnt(0)
	s_barrier
	v_mfma_f32_16x16x32_bf16 v[60:63], v[150:153], v[166:169], v[60:63]
	v_mfma_f32_16x16x32_bf16 v[56:59], v[158:161], v[166:169], v[56:59]
	v_mfma_f32_16x16x32_bf16 v[44:47], v[150:153], v[174:177], v[44:47]
	v_mfma_f32_16x16x32_bf16 v[40:43], v[158:161], v[174:177], v[40:43]
	v_mfma_f32_16x16x32_bf16 v[28:31], v[150:153], v[182:185], v[28:31]
	v_mfma_f32_16x16x32_bf16 v[24:27], v[158:161], v[182:185], v[24:27]
	v_mfma_f32_16x16x32_bf16 v[12:15], v[150:153], v[190:193], v[12:15]
	v_mfma_f32_16x16x32_bf16 v[8:11], v[158:161], v[190:193], v[8:11]
	v_mfma_f32_16x16x32_bf16 v[60:63], v[154:157], v[170:173], v[60:63]
	v_mfma_f32_16x16x32_bf16 v[56:59], v[162:165], v[170:173], v[56:59]
	v_mfma_f32_16x16x32_bf16 v[44:47], v[154:157], v[178:181], v[44:47]
	v_mfma_f32_16x16x32_bf16 v[40:43], v[162:165], v[178:181], v[40:43]
	v_mfma_f32_16x16x32_bf16 v[28:31], v[154:157], v[186:189], v[28:31]
	v_mfma_f32_16x16x32_bf16 v[24:27], v[162:165], v[186:189], v[24:27]
	v_mfma_f32_16x16x32_bf16 v[12:15], v[154:157], v[194:197], v[12:15]
	v_mfma_f32_16x16x32_bf16 v[8:11], v[162:165], v[194:197], v[8:11]
	v_mfma_f32_16x16x32_bf16 v[52:55], v[198:201], v[166:169], v[52:55]
	v_mfma_f32_16x16x32_bf16 v[48:51], v[206:209], v[166:169], v[48:51]
	v_mfma_f32_16x16x32_bf16 v[36:39], v[198:201], v[174:177], v[36:39]
	v_mfma_f32_16x16x32_bf16 v[32:35], v[206:209], v[174:177], v[32:35]
	v_mfma_f32_16x16x32_bf16 v[20:23], v[198:201], v[182:185], v[20:23]
	v_mfma_f32_16x16x32_bf16 v[16:19], v[206:209], v[182:185], v[16:19]
	v_mfma_f32_16x16x32_bf16 v[4:7], v[198:201], v[190:193], v[4:7]
	v_mfma_f32_16x16x32_bf16 v[0:3], v[206:209], v[190:193], v[0:3]
	v_mfma_f32_16x16x32_bf16 v[52:55], v[202:205], v[170:173], v[52:55]
	v_mfma_f32_16x16x32_bf16 v[48:51], v[210:213], v[170:173], v[48:51]
	v_mfma_f32_16x16x32_bf16 v[36:39], v[202:205], v[178:181], v[36:39]
	v_mfma_f32_16x16x32_bf16 v[32:35], v[210:213], v[178:181], v[32:35]
	v_mfma_f32_16x16x32_bf16 v[20:23], v[202:205], v[186:189], v[20:23]
	v_mfma_f32_16x16x32_bf16 v[16:19], v[210:213], v[186:189], v[16:19]
	v_mfma_f32_16x16x32_bf16 v[4:7], v[202:205], v[194:197], v[4:7]
	v_mfma_f32_16x16x32_bf16 v[0:3], v[210:213], v[194:197], v[0:3]
	s_barrier
; #define PG8_STAGE(bufoff, gbase, voff) do { _Pragma("unroll") for (int _i = 0; _i < 2; ++_i) \
;         __builtin_amdgcn_global_load_lds((const unsigned*)((const char*)(gbase) + (voff)[_i]), (PG8_LAS unsigned*)(lds + (bufoff) + ldsw + _i * 8192), 16, 0, 0); } while (0)
; #define PG8_LDA(dst, b, h) do { _Pragma("unroll") for (int m = 0; m < 4; ++m) _Pragma("unroll") for (int k = 0; k < 2; ++k) dst[m][k] = *(const PG8_LAS bf16x8*)(lds + PG8_SA(b, h) + aoff + m * 2048 + k * 1024); } while (0)
; #define PG8_LDB(dst, b, h) do { _Pragma("unroll") for (int n = 0; n < 2; ++n) _Pragma("unroll") for (int k = 0; k < 2; ++k) dst[n][k] = *(const PG8_LAS bf16x8*)(lds + PG8_SB(b, h) + boff + n * 2048 + k * 1024); } while (0)
; #define PG8_MMA(ai, bj, At, Bt) do { __builtin_amdgcn_s_setprio(1); _Pragma("unroll") for (int m = 0; m < 4; ++m) _Pragma("unroll") for (int n = 0; n < 2; ++n) _Pragma("unroll") for (int k = 0; k < 2; ++k) \
;         acc[ai][bj][m][n] = __builtin_amdgcn_mfma_f32_16x16x32_bf16(Bt[n][k], At[m][k], acc[ai][bj][m][n], 0, 0, 0); __builtin_amdgcn_s_setprio(0); } while (0)
; #define PG8_WAIT_V(n) asm volatile("s_waitcnt vmcnt(" #n ")" ::: "memory")
; #define PG8_WAIT_L(n) asm volatile("s_waitcnt lgkmcnt(" #n ")" ::: "memory")
; #define PG8_BAR __builtin_amdgcn_s_barrier()
; #define PG8_SCHED __builtin_amdgcn_sched_barrier(0)
; template <class Epi, class Sched>
; __device__ __forceinline__ void gemm_phase(PG8_LAS unsigned char* lds, const Gemm g, const Sched& S, const Epi& E) {
;     ...
;             PG8_LDB(B0, 1, 0); PG8_SCHED; PG8_LDA(At, 1, 0); PG8_STAGE(PG8_SA(0, 1), a2 + hstep, voffA);
;             PG8_WAIT_L(8); PG8_BAR; PG8_WAIT_L(0); PG8_MMA(0, 0, At, B0); PG8_BAR; PG8_SCHED;
;             PG8_LDB(B1, 1, 1); PG8_STAGE(PG8_SB(1, 0), b3, voffB);
;             PG8_BAR; PG8_WAIT_L(0); PG8_MMA(0, 1, At, B1); PG8_BAR;
;             PG8_LDA(At, 1, 1); PG8_STAGE(PG8_SA(1, 0), a3, voffA);
;             PG8_BAR; PG8_WAIT_L(0); PG8_MMA(1, 0, At, B0); PG8_BAR; PG8_SCHED;
;             PG8_STAGE(PG8_SB(1, 1), b3 + hstepB, voffB);
;             PG8_WAIT_V(6); PG8_BAR; PG8_MMA(1, 1, At, B1); PG8_BAR;
	s_add_i32 s70, 0, 0x18000
	v_add_u32_e32 v162, s70, v145
	ds_read_b128 v[150:153], v162
	ds_read_b128 v[154:157], v162 offset:1024
	ds_read_b128 v[158:161], v162 offset:2048
	ds_read_b128 v[162:165], v162 offset:3072
	s_add_u32 s50, s50, 0x80000
	s_addc_u32 s51, s51, 0
	s_mov_b32 m0, s56
	ds_read_b128 v[166:169], v148 offset:32768
	ds_read_b128 v[170:173], v148 offset:33792
	ds_read_b128 v[174:177], v148 offset:34816
	ds_read_b128 v[178:181], v148 offset:35840
	ds_read_b128 v[182:185], v148 offset:36864
	ds_read_b128 v[186:189], v148 offset:37888
	ds_read_b128 v[190:193], v148 offset:38912
	ds_read_b128 v[194:197], v148 offset:39936
	global_load_lds_dwordx4 v130, s[50:51]
	s_mov_b32 m0, s57
	s_nop 0
	global_load_lds_dwordx4 v134, s[50:51]
	s_add_i32 s71, 0, 0x1c000
	s_add_u32 s50, s48, 0x8000
	s_addc_u32 s51, s49, 0
	s_add_i32 s70, s70, s53
	v_add_u32_e32 v210, s71, v145
	s_mov_b32 m0, s70
	ds_read_b128 v[198:201], v210
	ds_read_b128 v[202:205], v210 offset:1024
	ds_read_b128 v[206:209], v210 offset:2048
	ds_read_b128 v[210:213], v210 offset:3072
	s_waitcnt vmcnt(8)
	s_waitcnt lgkmcnt(0)
	s_barrier
	v_mfma_f32_16x16x32_bf16 v[124:127], v[150:153], v[166:169], v[124:127]
	v_mfma_f32_16x16x32_bf16 v[120:123], v[158:161], v[166:169], v[120:123]
	v_mfma_f32_16x16x32_bf16 v[108:111], v[150:153], v[174:177], v[108:111]
	v_mfma_f32_16x16x32_bf16 v[104:107], v[158:161], v[174:177], v[104:107]
	v_mfma_f32_16x16x32_bf16 v[92:95], v[150:153], v[182:185], v[92:95]
	v_mfma_f32_16x16x32_bf16 v[88:91], v[158:161], v[182:185], v[88:91]
	v_mfma_f32_16x16x32_bf16 v[76:79], v[150:153], v[190:193], v[76:79]
	v_mfma_f32_16x16x32_bf16 v[72:75], v[158:161], v[190:193], v[72:75]
	v_mfma_f32_16x16x32_bf16 v[124:127], v[154:157], v[170:173], v[124:127]
	v_mfma_f32_16x16x32_bf16 v[120:123], v[162:165], v[170:173], v[120:123]
	v_mfma_f32_16x16x32_bf16 v[108:111], v[154:157], v[178:181], v[108:111]
	v_mfma_f32_16x16x32_bf16 v[104:107], v[162:165], v[178:181], v[104:107]
	v_mfma_f32_16x16x32_bf16 v[92:95], v[154:157], v[186:189], v[92:95]
	v_mfma_f32_16x16x32_bf16 v[88:91], v[162:165], v[186:189], v[88:91]
	v_mfma_f32_16x16x32_bf16 v[76:79], v[154:157], v[194:197], v[76:79]
	v_mfma_f32_16x16x32_bf16 v[72:75], v[162:165], v[194:197], v[72:75]
	v_mfma_f32_16x16x32_bf16 v[116:119], v[198:201], v[166:169], v[116:119]
	v_mfma_f32_16x16x32_bf16 v[112:115], v[206:209], v[166:169], v[112:115]
	v_mfma_f32_16x16x32_bf16 v[100:103], v[198:201], v[174:177], v[100:103]
	v_mfma_f32_16x16x32_bf16 v[96:99], v[206:209], v[174:177], v[96:99]
	v_mfma_f32_16x16x32_bf16 v[84:87], v[198:201], v[182:185], v[84:87]
	v_mfma_f32_16x16x32_bf16 v[80:83], v[206:209], v[182:185], v[80:83]
	v_mfma_f32_16x16x32_bf16 v[68:71], v[198:201], v[190:193], v[68:71]
	v_mfma_f32_16x16x32_bf16 v[64:67], v[206:209], v[190:193], v[64:67]
	v_mfma_f32_16x16x32_bf16 v[116:119], v[202:205], v[170:173], v[116:119]
	v_mfma_f32_16x16x32_bf16 v[112:115], v[210:213], v[170:173], v[112:115]
	v_mfma_f32_16x16x32_bf16 v[100:103], v[202:205], v[178:181], v[100:103]
	v_mfma_f32_16x16x32_bf16 v[96:99], v[210:213], v[178:181], v[96:99]
	v_mfma_f32_16x16x32_bf16 v[84:87], v[202:205], v[186:189], v[84:87]
	v_mfma_f32_16x16x32_bf16 v[80:83], v[210:213], v[186:189], v[80:83]
	v_mfma_f32_16x16x32_bf16 v[68:71], v[202:205], v[194:197], v[68:71]
	v_mfma_f32_16x16x32_bf16 v[64:67], v[210:213], v[194:197], v[64:67]
	s_barrier
	global_load_lds_dwordx4 v128, s[50:51]
	s_add_i32 m0, s70, 0x2000
	s_nop 0
	global_load_lds_dwordx4 v132, s[50:51]
	s_mov_b32 m0, s59
	v_lshl_add_u64 v[214:215], v[214:215], 0, s[12:13]
	ds_read_b128 v[166:169], v148 offset:49152
	ds_read_b128 v[170:173], v148 offset:50176
	ds_read_b128 v[174:177], v148 offset:51200
	ds_read_b128 v[178:181], v148 offset:52224
	ds_read_b128 v[182:185], v148 offset:53248
	ds_read_b128 v[186:189], v148 offset:54272
	ds_read_b128 v[190:193], v148 offset:55296
	ds_read_b128 v[194:197], v148 offset:56320
	global_load_lds_dwordx4 v[214:215], off
	v_lshl_add_u64 v[214:215], v[216:217], 0, s[12:13]
	s_mov_b32 m0, s60
	s_nop 0
	global_load_lds_dwordx4 v[214:215], off
	s_add_u32 s48, s48, 0xc000
	s_addc_u32 s49, s49, 0
	s_add_i32 s50, s71, s53
	s_mov_b32 m0, s50
	s_nop 0
	global_load_lds_dwordx4 v128, s[48:49]
	s_add_i32 m0, s50, 0x2000
	s_nop 0
	global_load_lds_dwordx4 v132, s[48:49]
	s_add_i32 s69, s69, 2
	s_add_u32 s67, s67, 0x10000
	s_addc_u32 s68, s68, 0
	s_add_u32 s6, s6, 0x100
	s_addc_u32 s7, s7, 0
	s_cmp_gt_u32 s69, 29
	s_waitcnt vmcnt(8)
	s_waitcnt lgkmcnt(0)
	s_barrier
	v_mfma_f32_16x16x32_bf16 v[60:63], v[150:153], v[166:169], v[60:63]
	v_mfma_f32_16x16x32_bf16 v[56:59], v[158:161], v[166:169], v[56:59]
	v_mfma_f32_16x16x32_bf16 v[44:47], v[150:153], v[174:177], v[44:47]
	v_mfma_f32_16x16x32_bf16 v[40:43], v[158:161], v[174:177], v[40:43]
	v_mfma_f32_16x16x32_bf16 v[28:31], v[150:153], v[182:185], v[28:31]
	v_mfma_f32_16x16x32_bf16 v[24:27], v[158:161], v[182:185], v[24:27]
	v_mfma_f32_16x16x32_bf16 v[12:15], v[150:153], v[190:193], v[12:15]
	v_mfma_f32_16x16x32_bf16 v[8:11], v[158:161], v[190:193], v[8:11]
	v_mfma_f32_16x16x32_bf16 v[60:63], v[154:157], v[170:173], v[60:63]
	v_mfma_f32_16x16x32_bf16 v[56:59], v[162:165], v[170:173], v[56:59]
	v_mfma_f32_16x16x32_bf16 v[44:47], v[154:157], v[178:181], v[44:47]
	v_mfma_f32_16x16x32_bf16 v[40:43], v[162:165], v[178:181], v[40:43]
	v_mfma_f32_16x16x32_bf16 v[28:31], v[154:157], v[186:189], v[28:31]
	v_mfma_f32_16x16x32_bf16 v[24:27], v[162:165], v[186:189], v[24:27]
	v_mfma_f32_16x16x32_bf16 v[12:15], v[154:157], v[194:197], v[12:15]
	v_mfma_f32_16x16x32_bf16 v[8:11], v[162:165], v[194:197], v[8:11]
	v_mfma_f32_16x16x32_bf16 v[52:55], v[198:201], v[166:169], v[52:55]
	v_mfma_f32_16x16x32_bf16 v[48:51], v[206:209], v[166:169], v[48:51]
	v_mfma_f32_16x16x32_bf16 v[36:39], v[198:201], v[174:177], v[36:39]
	v_mfma_f32_16x16x32_bf16 v[32:35], v[206:209], v[174:177], v[32:35]
	v_mfma_f32_16x16x32_bf16 v[20:23], v[198:201], v[182:185], v[20:23]
	v_mfma_f32_16x16x32_bf16 v[16:19], v[206:209], v[182:185], v[16:19]
	v_mfma_f32_16x16x32_bf16 v[4:7], v[198:201], v[190:193], v[4:7]
	v_mfma_f32_16x16x32_bf16 v[0:3], v[206:209], v[190:193], v[0:3]
	v_mfma_f32_16x16x32_bf16 v[52:55], v[202:205], v[170:173], v[52:55]
	v_mfma_f32_16x16x32_bf16 v[48:51], v[210:213], v[170:173], v[48:51]
	v_mfma_f32_16x16x32_bf16 v[36:39], v[202:205], v[178:181], v[36:39]
	v_mfma_f32_16x16x32_bf16 v[32:35], v[210:213], v[178:181], v[32:35]
	v_mfma_f32_16x16x32_bf16 v[20:23], v[202:205], v[186:189], v[20:23]
	v_mfma_f32_16x16x32_bf16 v[16:19], v[210:213], v[186:189], v[16:19]
	v_mfma_f32_16x16x32_bf16 v[4:7], v[202:205], v[194:197], v[4:7]
	v_mfma_f32_16x16x32_bf16 v[0:3], v[210:213], v[194:197], v[0:3]
	s_cbranch_scc1 .Lunit_exit_2
	s_barrier
	s_branch .LBB0_280

; #define PG8_STAGE(bufoff, gbase, voff) do { _Pragma("unroll") for (int _i = 0; _i < 2; ++_i) \
;         __builtin_amdgcn_global_load_lds((const unsigned*)((const char*)(gbase) + (voff)[_i]), (PG8_LAS unsigned*)(lds + (bufoff) + ldsw + _i * 8192), 16, 0, 0); } while (0)
; #define PG8_LDA(dst, b, h) do { _Pragma("unroll") for (int m = 0; m < 4; ++m) _Pragma("unroll") for (int k = 0; k < 2; ++k) dst[m][k] = *(const PG8_LAS bf16x8*)(lds + PG8_SA(b, h) + aoff + m * 2048 + k * 1024); } while (0)
; #define PG8_LDB(dst, b, h) do { _Pragma("unroll") for (int n = 0; n < 2; ++n) _Pragma("unroll") for (int k = 0; k < 2; ++k) dst[n][k] = *(const PG8_LAS bf16x8*)(lds + PG8_SB(b, h) + boff + n * 2048 + k * 1024); } while (0)
; #define PG8_MMA(ai, bj, At, Bt) do { __builtin_amdgcn_s_setprio(1); _Pragma("unroll") for (int m = 0; m < 4; ++m) _Pragma("unroll") for (int n = 0; n < 2; ++n) _Pragma("unroll") for (int k = 0; k < 2; ++k) \
;         acc[ai][bj][m][n] = __builtin_amdgcn_mfma_f32_16x16x32_bf16(Bt[n][k], At[m][k], acc[ai][bj][m][n], 0, 0, 0); __builtin_amdgcn_s_setprio(0); } while (0)
; #define PG8_WAIT_V(n) asm volatile("s_waitcnt vmcnt(" #n ")" ::: "memory")
; template <class Epi, class Sched>
; __device__ __forceinline__ void gemm_phase(PG8_LAS unsigned char* lds, const Gemm g, const Sched& S, const Epi& E) {
;     ...
;         for (int t = 0; t < nt; t += 2) {
;             const bool last = (t == nt - 2);
;             const char* a1 = cA + (size_t)(t + 1) * kstep;
;             const char* a2 = last ? nA : cA + (size_t)(t + 2) * kstep; const char* b2 = last ? nB : cB + (size_t)(t + 2) * kstepB;
;             const char* a3 = a2 + kstep; const char* b3 = b2 + kstepB;
;             if (last && has_next) S.a_ready(nxt);
;             PG8_LDB(B0, 0, 0); PG8_SCHED; PG8_LDA(At, 0, 0); PG8_STAGE(PG8_SA(1, 1), a1 + hstep, voffA);
;             PG8_WAIT_L(8); PG8_BAR; PG8_WAIT_L(0); PG8_MMA(0, 0, At, B0); PG8_BAR; PG8_SCHED;
;             PG8_LDB(B1, 0, 1); PG8_STAGE(PG8_SB(0, 0), b2, voffB);
;             PG8_BAR; PG8_WAIT_L(0); PG8_MMA(0, 1, At, B1); PG8_BAR;
;             PG8_LDA(At, 0, 1); PG8_STAGE(PG8_SA(0, 0), a2, voffA);
;             PG8_BAR; PG8_WAIT_L(0); PG8_MMA(1, 0, At, B0); PG8_BAR; PG8_SCHED;
;             PG8_STAGE(PG8_SB(0, 1), b2 + hstepB, voffB);
;             PG8_WAIT_V(6); PG8_BAR; PG8_MMA(1, 1, At, B1); PG8_BAR;
.Lhalf_skip_y_3:
.LBB0_397:
	ds_read_b128 v[142:145], v150
	ds_read_b128 v[154:157], v150 offset:1024
	ds_read_b128 v[158:161], v150 offset:2048
	ds_read_b128 v[162:165], v150 offset:3072
	s_add_u32 s26, s24, 0xfff80080
	s_addc_u32 s27, s25, -1
	s_cmp_eq_u32 s66, 28
	s_cselect_b32 s29, s5, s27
	s_cselect_b32 s28, s15, s26
	s_cselect_b32 s27, s17, s65
	s_cselect_b32 s26, s23, s64
	s_add_i32 m0, s48, 0xc000
	ds_read_b128 v[166:169], v151
	ds_read_b128 v[170:173], v151 offset:1024
	ds_read_b128 v[174:177], v151 offset:2048
	ds_read_b128 v[178:181], v151 offset:3072
	ds_read_b128 v[182:185], v151 offset:4096
	ds_read_b128 v[186:189], v151 offset:5120
	ds_read_b128 v[190:193], v151 offset:6144
	ds_read_b128 v[194:197], v151 offset:7168
	global_load_lds_dwordx4 v138, s[24:25]
	s_add_i32 m0, s48, 0xe000
	s_nop 0
	global_load_lds_dwordx4 v140, s[24:25]
	s_add_i32 s67, s59, s39
	s_mov_b32 m0, s67
	ds_read_b128 v[198:201], v152
	ds_read_b128 v[202:205], v152 offset:1024
	ds_read_b128 v[206:209], v152 offset:2048
	ds_read_b128 v[210:213], v152 offset:3072
	s_waitcnt vmcnt(8)
	s_waitcnt lgkmcnt(0)
	s_barrier
	v_mfma_f32_16x16x32_bf16 v[124:127], v[142:145], v[166:169], v[124:127]
	v_mfma_f32_16x16x32_bf16 v[120:123], v[158:161], v[166:169], v[120:123]
	v_mfma_f32_16x16x32_bf16 v[108:111], v[142:145], v[174:177], v[108:111]
	v_mfma_f32_16x16x32_bf16 v[104:107], v[158:161], v[174:177], v[104:107]
	v_mfma_f32_16x16x32_bf16 v[92:95], v[142:145], v[182:185], v[92:95]
	v_mfma_f32_16x16x32_bf16 v[88:91], v[158:161], v[182:185], v[88:91]
	v_mfma_f32_16x16x32_bf16 v[76:79], v[142:145], v[190:193], v[76:79]
	v_mfma_f32_16x16x32_bf16 v[72:75], v[158:161], v[190:193], v[72:75]
	v_mfma_f32_16x16x32_bf16 v[124:127], v[154:157], v[170:173], v[124:127]
	v_mfma_f32_16x16x32_bf16 v[120:123], v[162:165], v[170:173], v[120:123]
	v_mfma_f32_16x16x32_bf16 v[108:111], v[154:157], v[178:181], v[108:111]
	v_mfma_f32_16x16x32_bf16 v[104:107], v[162:165], v[178:181], v[104:107]
	v_mfma_f32_16x16x32_bf16 v[92:95], v[154:157], v[186:189], v[92:95]
	v_mfma_f32_16x16x32_bf16 v[88:91], v[162:165], v[186:189], v[88:91]
	v_mfma_f32_16x16x32_bf16 v[76:79], v[154:157], v[194:197], v[76:79]
	v_mfma_f32_16x16x32_bf16 v[72:75], v[162:165], v[194:197], v[72:75]
	v_mfma_f32_16x16x32_bf16 v[116:119], v[198:201], v[166:169], v[116:119]
	v_mfma_f32_16x16x32_bf16 v[112:115], v[206:209], v[166:169], v[112:115]
	v_mfma_f32_16x16x32_bf16 v[100:103], v[198:201], v[174:177], v[100:103]
	v_mfma_f32_16x16x32_bf16 v[96:99], v[206:209], v[174:177], v[96:99]
	v_mfma_f32_16x16x32_bf16 v[84:87], v[198:201], v[182:185], v[84:87]
	v_mfma_f32_16x16x32_bf16 v[80:83], v[206:209], v[182:185], v[80:83]
	v_mfma_f32_16x16x32_bf16 v[68:71], v[198:201], v[190:193], v[68:71]
	v_mfma_f32_16x16x32_bf16 v[64:67], v[206:209], v[190:193], v[64:67]
	v_mfma_f32_16x16x32_bf16 v[116:119], v[202:205], v[170:173], v[116:119]
	v_mfma_f32_16x16x32_bf16 v[112:115], v[210:213], v[170:173], v[112:115]
	v_mfma_f32_16x16x32_bf16 v[100:103], v[202:205], v[178:181], v[100:103]
	v_mfma_f32_16x16x32_bf16 v[96:99], v[210:213], v[178:181], v[96:99]
	v_mfma_f32_16x16x32_bf16 v[84:87], v[202:205], v[186:189], v[84:87]
	v_mfma_f32_16x16x32_bf16 v[80:83], v[210:213], v[186:189], v[80:83]
	v_mfma_f32_16x16x32_bf16 v[68:71], v[202:205], v[194:197], v[68:71]
	v_mfma_f32_16x16x32_bf16 v[64:67], v[210:213], v[194:197], v[64:67]
	s_barrier
	global_load_lds_dwordx4 v128, s[26:27]
	s_add_i32 m0, s67, 0x2000
	s_nop 0
	global_load_lds_dwordx4 v132, s[26:27]
	s_mov_b32 m0, s48
	v_lshl_add_u64 v[214:215], s[28:29], 0, v[130:131]
	ds_read_b128 v[166:169], v151 offset:16384
	ds_read_b128 v[170:173], v151 offset:17408
	ds_read_b128 v[174:177], v151 offset:18432
	ds_read_b128 v[178:181], v151 offset:19456
	ds_read_b128 v[182:185], v151 offset:20480
	ds_read_b128 v[186:189], v151 offset:21504
	ds_read_b128 v[190:193], v151 offset:22528
	ds_read_b128 v[194:197], v151 offset:23552
	global_load_lds_dwordx4 v[214:215], off
	v_lshl_add_u64 v[216:217], s[28:29], 0, v[134:135]
	s_mov_b32 m0, s49
	s_nop 0
	global_load_lds_dwordx4 v[216:217], off
	s_add_u32 s68, s26, 0x4000
	s_addc_u32 s69, s27, 0
	s_add_i32 s67, s60, s39
	s_mov_b32 m0, s67
	s_nop 0
	global_load_lds_dwordx4 v128, s[68:69]
	s_add_i32 m0, s67, 0x2000
	s_nop 0
	global_load_lds_dwordx4 v132, s[68:69]
	s_waitcnt vmcnt(8)
	s_waitcnt lgkmcnt(0)
	s_barrier
	v_mfma_f32_16x16x32_bf16 v[60:63], v[142:145], v[166:169], v[60:63]
	v_mfma_f32_16x16x32_bf16 v[56:59], v[158:161], v[166:169], v[56:59]
	v_mfma_f32_16x16x32_bf16 v[44:47], v[142:145], v[174:177], v[44:47]
	v_mfma_f32_16x16x32_bf16 v[40:43], v[158:161], v[174:177], v[40:43]
	v_mfma_f32_16x16x32_bf16 v[28:31], v[142:145], v[182:185], v[28:31]
	v_mfma_f32_16x16x32_bf16 v[24:27], v[158:161], v[182:185], v[24:27]
	v_mfma_f32_16x16x32_bf16 v[12:15], v[142:145], v[190:193], v[12:15]
	v_mfma_f32_16x16x32_bf16 v[8:11], v[158:161], v[190:193], v[8:11]
	v_mfma_f32_16x16x32_bf16 v[60:63], v[154:157], v[170:173], v[60:63]
	v_mfma_f32_16x16x32_bf16 v[56:59], v[162:165], v[170:173], v[56:59]
	v_mfma_f32_16x16x32_bf16 v[44:47], v[154:157], v[178:181], v[44:47]
	v_mfma_f32_16x16x32_bf16 v[40:43], v[162:165], v[178:181], v[40:43]
	v_mfma_f32_16x16x32_bf16 v[28:31], v[154:157], v[186:189], v[28:31]
	v_mfma_f32_16x16x32_bf16 v[24:27], v[162:165], v[186:189], v[24:27]
	v_mfma_f32_16x16x32_bf16 v[12:15], v[154:157], v[194:197], v[12:15]
	v_mfma_f32_16x16x32_bf16 v[8:11], v[162:165], v[194:197], v[8:11]
	v_mfma_f32_16x16x32_bf16 v[52:55], v[198:201], v[166:169], v[52:55]
	v_mfma_f32_16x16x32_bf16 v[48:51], v[206:209], v[166:169], v[48:51]
	v_mfma_f32_16x16x32_bf16 v[36:39], v[198:201], v[174:177], v[36:39]
	v_mfma_f32_16x16x32_bf16 v[32:35], v[206:209], v[174:177], v[32:35]
	v_mfma_f32_16x16x32_bf16 v[20:23], v[198:201], v[182:185], v[20:23]
	v_mfma_f32_16x16x32_bf16 v[16:19], v[206:209], v[182:185], v[16:19]
	v_mfma_f32_16x16x32_bf16 v[4:7], v[198:201], v[190:193], v[4:7]
	v_mfma_f32_16x16x32_bf16 v[0:3], v[206:209], v[190:193], v[0:3]
	v_mfma_f32_16x16x32_bf16 v[52:55], v[202:205], v[170:173], v[52:55]
	v_mfma_f32_16x16x32_bf16 v[48:51], v[210:213], v[170:173], v[48:51]
	v_mfma_f32_16x16x32_bf16 v[36:39], v[202:205], v[178:181], v[36:39]
	v_mfma_f32_16x16x32_bf16 v[32:35], v[210:213], v[178:181], v[32:35]
	v_mfma_f32_16x16x32_bf16 v[20:23], v[202:205], v[186:189], v[20:23]
	v_mfma_f32_16x16x32_bf16 v[16:19], v[210:213], v[186:189], v[16:19]
	v_mfma_f32_16x16x32_bf16 v[4:7], v[202:205], v[194:197], v[4:7]
	v_mfma_f32_16x16x32_bf16 v[0:3], v[210:213], v[194:197], v[0:3]
	s_barrier
; #define PG8_STAGE(bufoff, gbase, voff) do { _Pragma("unroll") for (int _i = 0; _i < 2; ++_i) \
;         __builtin_amdgcn_global_load_lds((const unsigned*)((const char*)(gbase) + (voff)[_i]), (PG8_LAS unsigned*)(lds + (bufoff) + ldsw + _i * 8192), 16, 0, 0); } while (0)
; #define PG8_LDA(dst, b, h) do { _Pragma("unroll") for (int m = 0; m < 4; ++m) _Pragma("unroll") for (int k = 0; k < 2; ++k) dst[m][k] = *(const PG8_LAS bf16x8*)(lds + PG8_SA(b, h) + aoff + m * 2048 + k * 1024); } while (0)
; #define PG8_LDB(dst, b, h) do { _Pragma("unroll") for (int n = 0; n < 2; ++n) _Pragma("unroll") for (int k = 0; k < 2; ++k) dst[n][k] = *(const PG8_LAS bf16x8*)(lds + PG8_SB(b, h) + boff + n * 2048 + k * 1024); } while (0)
; #define PG8_MMA(ai, bj, At, Bt) do { __builtin_amdgcn_s_setprio(1); _Pragma("unroll") for (int m = 0; m < 4; ++m) _Pragma("unroll") for (int n = 0; n < 2; ++n) _Pragma("unroll") for (int k = 0; k < 2; ++k) \
;         acc[ai][bj][m][n] = __builtin_amdgcn_mfma_f32_16x16x32_bf16(Bt[n][k], At[m][k], acc[ai][bj][m][n], 0, 0, 0); __builtin_amdgcn_s_setprio(0); } while (0)
; #define PG8_WAIT_V(n) asm volatile("s_waitcnt vmcnt(" #n ")" ::: "memory")
; #define PG8_WAIT_L(n) asm volatile("s_waitcnt lgkmcnt(" #n ")" ::: "memory")
; #define PG8_BAR __builtin_amdgcn_s_barrier()
; #define PG8_SCHED __builtin_amdgcn_sched_barrier(0)
; template <class Epi, class Sched>
; __device__ __forceinline__ void gemm_phase(PG8_LAS unsigned char* lds, const Gemm g, const Sched& S, const Epi& E) {
;     ...
;             PG8_LDB(B0, 1, 0); PG8_SCHED; PG8_LDA(At, 1, 0); PG8_STAGE(PG8_SA(0, 1), a2 + hstep, voffA);
;             PG8_WAIT_L(8); PG8_BAR; PG8_WAIT_L(0); PG8_MMA(0, 0, At, B0); PG8_BAR; PG8_SCHED;
;             PG8_LDB(B1, 1, 1); PG8_STAGE(PG8_SB(1, 0), b3, voffB);
;             PG8_BAR; PG8_WAIT_L(0); PG8_MMA(0, 1, At, B1); PG8_BAR;
;             PG8_LDA(At, 1, 1); PG8_STAGE(PG8_SA(1, 0), a3, voffA);
;             PG8_BAR; PG8_WAIT_L(0); PG8_MMA(1, 0, At, B0); PG8_BAR; PG8_SCHED;
;             PG8_STAGE(PG8_SB(1, 1), b3 + hstepB, voffB);
;             PG8_WAIT_V(6); PG8_BAR; PG8_MMA(1, 1, At, B1); PG8_BAR;
	s_add_i32 s67, 0, 0x18000
	v_add_u32_e32 v136, s67, v148
	ds_read_b128 v[142:145], v136
	ds_read_b128 v[154:157], v136 offset:1024
	ds_read_b128 v[158:161], v136 offset:2048
	ds_read_b128 v[162:165], v136 offset:3072
	s_add_u32 s28, s28, 0x80000
	s_addc_u32 s29, s29, 0
	s_mov_b32 m0, s50
	ds_read_b128 v[166:169], v151 offset:32768
	ds_read_b128 v[170:173], v151 offset:33792
	ds_read_b128 v[174:177], v151 offset:34816
	ds_read_b128 v[178:181], v151 offset:35840
	ds_read_b128 v[182:185], v151 offset:36864
	ds_read_b128 v[186:189], v151 offset:37888
	ds_read_b128 v[190:193], v151 offset:38912
	ds_read_b128 v[194:197], v151 offset:39936
	global_load_lds_dwordx4 v130, s[28:29]
	s_mov_b32 m0, s51
	s_nop 0
	global_load_lds_dwordx4 v134, s[28:29]
	s_add_i32 s68, 0, 0x1c000
	s_add_u32 s28, s26, 0x8000
	s_addc_u32 s29, s27, 0
	s_add_i32 s67, s67, s39
	v_add_u32_e32 v136, s68, v148
	s_mov_b32 m0, s67
	ds_read_b128 v[198:201], v136
	ds_read_b128 v[202:205], v136 offset:1024
	ds_read_b128 v[206:209], v136 offset:2048
	ds_read_b128 v[210:213], v136 offset:3072
	s_waitcnt vmcnt(8)
	s_waitcnt lgkmcnt(0)
	s_barrier
	v_mfma_f32_16x16x32_bf16 v[124:127], v[142:145], v[166:169], v[124:127]
	v_mfma_f32_16x16x32_bf16 v[120:123], v[158:161], v[166:169], v[120:123]
	v_mfma_f32_16x16x32_bf16 v[108:111], v[142:145], v[174:177], v[108:111]
	v_mfma_f32_16x16x32_bf16 v[104:107], v[158:161], v[174:177], v[104:107]
	v_mfma_f32_16x16x32_bf16 v[92:95], v[142:145], v[182:185], v[92:95]
	v_mfma_f32_16x16x32_bf16 v[88:91], v[158:161], v[182:185], v[88:91]
	v_mfma_f32_16x16x32_bf16 v[76:79], v[142:145], v[190:193], v[76:79]
	v_mfma_f32_16x16x32_bf16 v[72:75], v[158:161], v[190:193], v[72:75]
	v_mfma_f32_16x16x32_bf16 v[124:127], v[154:157], v[170:173], v[124:127]
	v_mfma_f32_16x16x32_bf16 v[120:123], v[162:165], v[170:173], v[120:123]
	v_mfma_f32_16x16x32_bf16 v[108:111], v[154:157], v[178:181], v[108:111]
	v_mfma_f32_16x16x32_bf16 v[104:107], v[162:165], v[178:181], v[104:107]
	v_mfma_f32_16x16x32_bf16 v[92:95], v[154:157], v[186:189], v[92:95]
	v_mfma_f32_16x16x32_bf16 v[88:91], v[162:165], v[186:189], v[88:91]
	v_mfma_f32_16x16x32_bf16 v[76:79], v[154:157], v[194:197], v[76:79]
	v_mfma_f32_16x16x32_bf16 v[72:75], v[162:165], v[194:197], v[72:75]
	v_mfma_f32_16x16x32_bf16 v[116:119], v[198:201], v[166:169], v[116:119]
	v_mfma_f32_16x16x32_bf16 v[112:115], v[206:209], v[166:169], v[112:115]
	v_mfma_f32_16x16x32_bf16 v[100:103], v[198:201], v[174:177], v[100:103]
	v_mfma_f32_16x16x32_bf16 v[96:99], v[206:209], v[174:177], v[96:99]
	v_mfma_f32_16x16x32_bf16 v[84:87], v[198:201], v[182:185], v[84:87]
	v_mfma_f32_16x16x32_bf16 v[80:83], v[206:209], v[182:185], v[80:83]
	v_mfma_f32_16x16x32_bf16 v[68:71], v[198:201], v[190:193], v[68:71]
	v_mfma_f32_16x16x32_bf16 v[64:67], v[206:209], v[190:193], v[64:67]
	v_mfma_f32_16x16x32_bf16 v[116:119], v[202:205], v[170:173], v[116:119]
	v_mfma_f32_16x16x32_bf16 v[112:115], v[210:213], v[170:173], v[112:115]
	v_mfma_f32_16x16x32_bf16 v[100:103], v[202:205], v[178:181], v[100:103]
	v_mfma_f32_16x16x32_bf16 v[96:99], v[210:213], v[178:181], v[96:99]
	v_mfma_f32_16x16x32_bf16 v[84:87], v[202:205], v[186:189], v[84:87]
	v_mfma_f32_16x16x32_bf16 v[80:83], v[210:213], v[186:189], v[80:83]
	v_mfma_f32_16x16x32_bf16 v[68:71], v[202:205], v[194:197], v[68:71]
	v_mfma_f32_16x16x32_bf16 v[64:67], v[210:213], v[194:197], v[64:67]
	s_barrier
	global_load_lds_dwordx4 v128, s[28:29]
	s_add_i32 m0, s67, 0x2000
	s_nop 0
	global_load_lds_dwordx4 v132, s[28:29]
	s_mov_b32 m0, s55
	v_lshl_add_u64 v[214:215], v[214:215], 0, s[10:11]
	ds_read_b128 v[166:169], v151 offset:49152
	ds_read_b128 v[170:173], v151 offset:50176
	ds_read_b128 v[174:177], v151 offset:51200
	ds_read_b128 v[178:181], v151 offset:52224
	ds_read_b128 v[182:185], v151 offset:53248
	ds_read_b128 v[186:189], v151 offset:54272
	ds_read_b128 v[190:193], v151 offset:55296
	ds_read_b128 v[194:197], v151 offset:56320
	global_load_lds_dwordx4 v[214:215], off
	v_lshl_add_u64 v[214:215], v[216:217], 0, s[10:11]
	s_mov_b32 m0, s56
	s_nop 0
	global_load_lds_dwordx4 v[214:215], off
	s_add_u32 s26, s26, 0xc000
	s_addc_u32 s27, s27, 0
	s_add_i32 s28, s68, s39
	s_mov_b32 m0, s28
	s_nop 0
	global_load_lds_dwordx4 v128, s[26:27]
	s_add_i32 m0, s28, 0x2000
	s_nop 0
	global_load_lds_dwordx4 v132, s[26:27]
	s_add_i32 s66, s66, 2
	s_add_u32 s64, s64, 0x10000
	s_addc_u32 s65, s65, 0
	s_add_u32 s24, s24, 0x100
	s_addc_u32 s25, s25, 0
	s_cmp_gt_u32 s66, 29
	s_waitcnt vmcnt(8)
	s_waitcnt lgkmcnt(0)
	s_barrier
	v_mfma_f32_16x16x32_bf16 v[60:63], v[142:145], v[166:169], v[60:63]
	v_mfma_f32_16x16x32_bf16 v[56:59], v[158:161], v[166:169], v[56:59]
	v_mfma_f32_16x16x32_bf16 v[44:47], v[142:145], v[174:177], v[44:47]
	v_mfma_f32_16x16x32_bf16 v[40:43], v[158:161], v[174:177], v[40:43]
	v_mfma_f32_16x16x32_bf16 v[28:31], v[142:145], v[182:185], v[28:31]
	v_mfma_f32_16x16x32_bf16 v[24:27], v[158:161], v[182:185], v[24:27]
	v_mfma_f32_16x16x32_bf16 v[12:15], v[142:145], v[190:193], v[12:15]
	v_mfma_f32_16x16x32_bf16 v[8:11], v[158:161], v[190:193], v[8:11]
	v_mfma_f32_16x16x32_bf16 v[60:63], v[154:157], v[170:173], v[60:63]
	v_mfma_f32_16x16x32_bf16 v[56:59], v[162:165], v[170:173], v[56:59]
	v_mfma_f32_16x16x32_bf16 v[44:47], v[154:157], v[178:181], v[44:47]
	v_mfma_f32_16x16x32_bf16 v[40:43], v[162:165], v[178:181], v[40:43]
	v_mfma_f32_16x16x32_bf16 v[28:31], v[154:157], v[186:189], v[28:31]
	v_mfma_f32_16x16x32_bf16 v[24:27], v[162:165], v[186:189], v[24:27]
	v_mfma_f32_16x16x32_bf16 v[12:15], v[154:157], v[194:197], v[12:15]
	v_mfma_f32_16x16x32_bf16 v[8:11], v[162:165], v[194:197], v[8:11]
	v_mfma_f32_16x16x32_bf16 v[52:55], v[198:201], v[166:169], v[52:55]
	v_mfma_f32_16x16x32_bf16 v[48:51], v[206:209], v[166:169], v[48:51]
	v_mfma_f32_16x16x32_bf16 v[36:39], v[198:201], v[174:177], v[36:39]
	v_mfma_f32_16x16x32_bf16 v[32:35], v[206:209], v[174:177], v[32:35]
	v_mfma_f32_16x16x32_bf16 v[20:23], v[198:201], v[182:185], v[20:23]
	v_mfma_f32_16x16x32_bf16 v[16:19], v[206:209], v[182:185], v[16:19]
	v_mfma_f32_16x16x32_bf16 v[4:7], v[198:201], v[190:193], v[4:7]
	v_mfma_f32_16x16x32_bf16 v[0:3], v[206:209], v[190:193], v[0:3]
	v_mfma_f32_16x16x32_bf16 v[52:55], v[202:205], v[170:173], v[52:55]
	v_mfma_f32_16x16x32_bf16 v[48:51], v[210:213], v[170:173], v[48:51]
	v_mfma_f32_16x16x32_bf16 v[36:39], v[202:205], v[178:181], v[36:39]
	v_mfma_f32_16x16x32_bf16 v[32:35], v[210:213], v[178:181], v[32:35]
	v_mfma_f32_16x16x32_bf16 v[20:23], v[202:205], v[186:189], v[20:23]
	v_mfma_f32_16x16x32_bf16 v[16:19], v[210:213], v[186:189], v[16:19]
	v_mfma_f32_16x16x32_bf16 v[4:7], v[202:205], v[194:197], v[4:7]
	v_mfma_f32_16x16x32_bf16 v[0:3], v[210:213], v[194:197], v[0:3]
	s_cbranch_scc1 .Lunit_exit_3
	s_barrier
	s_branch .LBB0_397

; #define PG8_STAGE(bufoff, gbase, voff) do { _Pragma("unroll") for (int _i = 0; _i < 2; ++_i) \
;         __builtin_amdgcn_global_load_lds((const unsigned*)((const char*)(gbase) + (voff)[_i]), (PG8_LAS unsigned*)(lds + (bufoff) + ldsw + _i * 8192), 16, 0, 0); } while (0)
; #define PG8_LDA(dst, b, h) do { _Pragma("unroll") for (int m = 0; m < 4; ++m) _Pragma("unroll") for (int k = 0; k < 2; ++k) dst[m][k] = *(const PG8_LAS bf16x8*)(lds + PG8_SA(b, h) + aoff + m * 2048 + k * 1024); } while (0)
; #define PG8_LDB(dst, b, h) do { _Pragma("unroll") for (int n = 0; n < 2; ++n) _Pragma("unroll") for (int k = 0; k < 2; ++k) dst[n][k] = *(const PG8_LAS bf16x8*)(lds + PG8_SB(b, h) + boff + n * 2048 + k * 1024); } while (0)
; #define PG8_MMA(ai, bj, At, Bt) do { __builtin_amdgcn_s_setprio(1); _Pragma("unroll") for (int m = 0; m < 4; ++m) _Pragma("unroll") for (int n = 0; n < 2; ++n) _Pragma("unroll") for (int k = 0; k < 2; ++k) \
;         acc[ai][bj][m][n] = __builtin_amdgcn_mfma_f32_16x16x32_bf16(Bt[n][k], At[m][k], acc[ai][bj][m][n], 0, 0, 0); __builtin_amdgcn_s_setprio(0); } while (0)
; #define PG8_WAIT_V(n) asm volatile("s_waitcnt vmcnt(" #n ")" ::: "memory")
; template <class Epi, class Sched>
; __device__ __forceinline__ void gemm_phase(PG8_LAS unsigned char* lds, const Gemm g, const Sched& S, const Epi& E) {
;     ...
;         for (int t = 0; t < nt; t += 2) {
;             const bool last = (t == nt - 2);
;             const char* a1 = cA + (size_t)(t + 1) * kstep;
;             const char* a2 = last ? nA : cA + (size_t)(t + 2) * kstep; const char* b2 = last ? nB : cB + (size_t)(t + 2) * kstepB;
;             const char* a3 = a2 + kstep; const char* b3 = b2 + kstepB;
;             if (last && has_next) S.a_ready(nxt);
;             PG8_LDB(B0, 0, 0); PG8_SCHED; PG8_LDA(At, 0, 0); PG8_STAGE(PG8_SA(1, 1), a1 + hstep, voffA);
;             PG8_WAIT_L(8); PG8_BAR; PG8_WAIT_L(0); PG8_MMA(0, 0, At, B0); PG8_BAR; PG8_SCHED;
;             PG8_LDB(B1, 0, 1); PG8_STAGE(PG8_SB(0, 0), b2, voffB);
;             PG8_BAR; PG8_WAIT_L(0); PG8_MMA(0, 1, At, B1); PG8_BAR;
;             PG8_LDA(At, 0, 1); PG8_STAGE(PG8_SA(0, 0), a2, voffA);
;             PG8_BAR; PG8_WAIT_L(0); PG8_MMA(1, 0, At, B0); PG8_BAR; PG8_SCHED;
;             PG8_STAGE(PG8_SB(0, 1), b2 + hstepB, voffB);
;             PG8_WAIT_V(6); PG8_BAR; PG8_MMA(1, 1, At, B1); PG8_BAR;
.Lhalf_skip_y_5:
.LBB0_783:
	ds_read_b128 v[128:131], v197
	ds_read_b128 v[132:135], v197 offset:1024
	ds_read_b128 v[136:139], v197 offset:2048
	ds_read_b128 v[140:143], v197 offset:3072
	s_add_u32 s30, s28, 0x100
	s_addc_u32 s31, s29, 0
	s_cmp_eq_u32 s69, 28
	s_cselect_b32 s39, s19, s31
	s_cselect_b32 s38, s65, s30
	s_cselect_b32 s37, s21, s68
	s_cselect_b32 s36, s66, s67
	v_lshl_add_u64 v[192:193], s[28:29], 0, v[172:173]
	s_add_i32 m0, s27, 0xc000
	ds_read_b128 v[144:147], v198
	ds_read_b128 v[148:151], v198 offset:1024
	ds_read_b128 v[152:155], v198 offset:2048
	ds_read_b128 v[156:159], v198 offset:3072
	ds_read_b128 v[160:163], v198 offset:4096
	ds_read_b128 v[180:183], v198 offset:5120
	ds_read_b128 v[184:187], v198 offset:6144
	ds_read_b128 v[188:191], v198 offset:7168
	global_load_lds_dwordx4 v[192:193], off
	v_lshl_add_u64 v[192:193], s[28:29], 0, v[174:175]
	s_add_i32 m0, s27, 0xe000
	s_nop 0
	global_load_lds_dwordx4 v[192:193], off
	s_add_i32 s28, s62, s54
	s_mov_b32 m0, s28
	ds_read_b128 v[200:203], v199
	ds_read_b128 v[204:207], v199 offset:1024
	ds_read_b128 v[208:211], v199 offset:2048
	ds_read_b128 v[212:215], v199 offset:3072
	s_waitcnt vmcnt(8)
	s_waitcnt lgkmcnt(0)
	s_barrier
	v_mfma_f32_16x16x32_bf16 v[124:127], v[128:131], v[144:147], v[124:127]
	v_mfma_f32_16x16x32_bf16 v[120:123], v[136:139], v[144:147], v[120:123]
	v_mfma_f32_16x16x32_bf16 v[116:119], v[128:131], v[152:155], v[116:119]
	v_mfma_f32_16x16x32_bf16 v[104:107], v[136:139], v[152:155], v[104:107]
	v_mfma_f32_16x16x32_bf16 v[92:95], v[128:131], v[160:163], v[92:95]
	v_mfma_f32_16x16x32_bf16 v[88:91], v[136:139], v[160:163], v[88:91]
	v_mfma_f32_16x16x32_bf16 v[76:79], v[128:131], v[184:187], v[76:79]
	v_mfma_f32_16x16x32_bf16 v[72:75], v[136:139], v[184:187], v[72:75]
	v_mfma_f32_16x16x32_bf16 v[124:127], v[132:135], v[148:151], v[124:127]
	v_mfma_f32_16x16x32_bf16 v[120:123], v[140:143], v[148:151], v[120:123]
	v_mfma_f32_16x16x32_bf16 v[116:119], v[132:135], v[156:159], v[116:119]
	v_mfma_f32_16x16x32_bf16 v[104:107], v[140:143], v[156:159], v[104:107]
	v_mfma_f32_16x16x32_bf16 v[92:95], v[132:135], v[180:183], v[92:95]
	v_mfma_f32_16x16x32_bf16 v[88:91], v[140:143], v[180:183], v[88:91]
	v_mfma_f32_16x16x32_bf16 v[76:79], v[132:135], v[188:191], v[76:79]
	v_mfma_f32_16x16x32_bf16 v[72:75], v[140:143], v[188:191], v[72:75]
	v_mfma_f32_16x16x32_bf16 v[112:115], v[200:203], v[144:147], v[112:115]
	v_mfma_f32_16x16x32_bf16 v[108:111], v[208:211], v[144:147], v[108:111]
	v_mfma_f32_16x16x32_bf16 v[100:103], v[200:203], v[152:155], v[100:103]
	v_mfma_f32_16x16x32_bf16 v[96:99], v[208:211], v[152:155], v[96:99]
	v_mfma_f32_16x16x32_bf16 v[84:87], v[200:203], v[160:163], v[84:87]
	v_mfma_f32_16x16x32_bf16 v[80:83], v[208:211], v[160:163], v[80:83]
	v_mfma_f32_16x16x32_bf16 v[68:71], v[200:203], v[184:187], v[68:71]
	v_mfma_f32_16x16x32_bf16 v[64:67], v[208:211], v[184:187], v[64:67]
	v_mfma_f32_16x16x32_bf16 v[112:115], v[204:207], v[148:151], v[112:115]
	v_mfma_f32_16x16x32_bf16 v[108:111], v[212:215], v[148:151], v[108:111]
	v_mfma_f32_16x16x32_bf16 v[100:103], v[204:207], v[156:159], v[100:103]
	v_mfma_f32_16x16x32_bf16 v[96:99], v[212:215], v[156:159], v[96:99]
	v_mfma_f32_16x16x32_bf16 v[84:87], v[204:207], v[180:183], v[84:87]
	v_mfma_f32_16x16x32_bf16 v[80:83], v[212:215], v[180:183], v[80:83]
	v_mfma_f32_16x16x32_bf16 v[68:71], v[204:207], v[188:191], v[68:71]
	v_mfma_f32_16x16x32_bf16 v[64:67], v[212:215], v[188:191], v[64:67]
	s_barrier
	global_load_lds_dwordx4 v164, s[36:37]
	s_add_i32 m0, s28, 0x2000
	s_nop 0
	global_load_lds_dwordx4 v168, s[36:37]
	s_mov_b32 m0, s27
	v_lshl_add_u64 v[192:193], s[38:39], 0, v[166:167]
	ds_read_b128 v[144:147], v198 offset:16384
	ds_read_b128 v[148:151], v198 offset:17408
	ds_read_b128 v[152:155], v198 offset:18432
	ds_read_b128 v[156:159], v198 offset:19456
	ds_read_b128 v[160:163], v198 offset:20480
	ds_read_b128 v[180:183], v198 offset:21504
	ds_read_b128 v[184:187], v198 offset:22528
	ds_read_b128 v[188:191], v198 offset:23552
	global_load_lds_dwordx4 v[192:193], off
	v_lshl_add_u64 v[216:217], s[38:39], 0, v[170:171]
	s_mov_b32 m0, s55
	s_nop 0
	global_load_lds_dwordx4 v[216:217], off
	s_add_u32 s28, s36, 0x4000
	s_addc_u32 s29, s37, 0
	s_add_i32 s70, s63, s54
	s_mov_b32 m0, s70
	s_nop 0
	global_load_lds_dwordx4 v164, s[28:29]
	s_add_i32 m0, s70, 0x2000
	s_nop 0
	global_load_lds_dwordx4 v168, s[28:29]
	s_waitcnt vmcnt(8)
	s_waitcnt lgkmcnt(0)
	s_barrier
	v_mfma_f32_16x16x32_bf16 v[60:63], v[128:131], v[144:147], v[60:63]
	v_mfma_f32_16x16x32_bf16 v[56:59], v[136:139], v[144:147], v[56:59]
	v_mfma_f32_16x16x32_bf16 v[44:47], v[128:131], v[152:155], v[44:47]
	v_mfma_f32_16x16x32_bf16 v[40:43], v[136:139], v[152:155], v[40:43]
	v_mfma_f32_16x16x32_bf16 v[28:31], v[128:131], v[160:163], v[28:31]
	v_mfma_f32_16x16x32_bf16 v[24:27], v[136:139], v[160:163], v[24:27]
	v_mfma_f32_16x16x32_bf16 v[12:15], v[128:131], v[184:187], v[12:15]
	v_mfma_f32_16x16x32_bf16 v[8:11], v[136:139], v[184:187], v[8:11]
	v_mfma_f32_16x16x32_bf16 v[60:63], v[132:135], v[148:151], v[60:63]
	v_mfma_f32_16x16x32_bf16 v[56:59], v[140:143], v[148:151], v[56:59]
	v_mfma_f32_16x16x32_bf16 v[44:47], v[132:135], v[156:159], v[44:47]
	v_mfma_f32_16x16x32_bf16 v[40:43], v[140:143], v[156:159], v[40:43]
	v_mfma_f32_16x16x32_bf16 v[28:31], v[132:135], v[180:183], v[28:31]
	v_mfma_f32_16x16x32_bf16 v[24:27], v[140:143], v[180:183], v[24:27]
	v_mfma_f32_16x16x32_bf16 v[12:15], v[132:135], v[188:191], v[12:15]
	v_mfma_f32_16x16x32_bf16 v[8:11], v[140:143], v[188:191], v[8:11]
	v_mfma_f32_16x16x32_bf16 v[52:55], v[200:203], v[144:147], v[52:55]
	v_mfma_f32_16x16x32_bf16 v[48:51], v[208:211], v[144:147], v[48:51]
	v_mfma_f32_16x16x32_bf16 v[36:39], v[200:203], v[152:155], v[36:39]
	v_mfma_f32_16x16x32_bf16 v[32:35], v[208:211], v[152:155], v[32:35]
	v_mfma_f32_16x16x32_bf16 v[20:23], v[200:203], v[160:163], v[20:23]
	v_mfma_f32_16x16x32_bf16 v[16:19], v[208:211], v[160:163], v[16:19]
	v_mfma_f32_16x16x32_bf16 v[4:7], v[200:203], v[184:187], v[4:7]
	v_mfma_f32_16x16x32_bf16 v[0:3], v[208:211], v[184:187], v[0:3]
	v_mfma_f32_16x16x32_bf16 v[52:55], v[204:207], v[148:151], v[52:55]
	v_mfma_f32_16x16x32_bf16 v[48:51], v[212:215], v[148:151], v[48:51]
	v_mfma_f32_16x16x32_bf16 v[36:39], v[204:207], v[156:159], v[36:39]
	v_mfma_f32_16x16x32_bf16 v[32:35], v[212:215], v[156:159], v[32:35]
	v_mfma_f32_16x16x32_bf16 v[20:23], v[204:207], v[180:183], v[20:23]
	v_mfma_f32_16x16x32_bf16 v[16:19], v[212:215], v[180:183], v[16:19]
	v_mfma_f32_16x16x32_bf16 v[4:7], v[204:207], v[188:191], v[4:7]
	v_mfma_f32_16x16x32_bf16 v[0:3], v[212:215], v[188:191], v[0:3]
	s_barrier
; #define PG8_STAGE(bufoff, gbase, voff) do { _Pragma("unroll") for (int _i = 0; _i < 2; ++_i) \
;         __builtin_amdgcn_global_load_lds((const unsigned*)((const char*)(gbase) + (voff)[_i]), (PG8_LAS unsigned*)(lds + (bufoff) + ldsw + _i * 8192), 16, 0, 0); } while (0)
; #define PG8_LDA(dst, b, h) do { _Pragma("unroll") for (int m = 0; m < 4; ++m) _Pragma("unroll") for (int k = 0; k < 2; ++k) dst[m][k] = *(const PG8_LAS bf16x8*)(lds + PG8_SA(b, h) + aoff + m * 2048 + k * 1024); } while (0)
; #define PG8_LDB(dst, b, h) do { _Pragma("unroll") for (int n = 0; n < 2; ++n) _Pragma("unroll") for (int k = 0; k < 2; ++k) dst[n][k] = *(const PG8_LAS bf16x8*)(lds + PG8_SB(b, h) + boff + n * 2048 + k * 1024); } while (0)
; #define PG8_MMA(ai, bj, At, Bt) do { __builtin_amdgcn_s_setprio(1); _Pragma("unroll") for (int m = 0; m < 4; ++m) _Pragma("unroll") for (int n = 0; n < 2; ++n) _Pragma("unroll") for (int k = 0; k < 2; ++k) \
;         acc[ai][bj][m][n] = __builtin_amdgcn_mfma_f32_16x16x32_bf16(Bt[n][k], At[m][k], acc[ai][bj][m][n], 0, 0, 0); __builtin_amdgcn_s_setprio(0); } while (0)
; #define PG8_WAIT_V(n) asm volatile("s_waitcnt vmcnt(" #n ")" ::: "memory")
; #define PG8_WAIT_L(n) asm volatile("s_waitcnt lgkmcnt(" #n ")" ::: "memory")
; #define PG8_BAR __builtin_amdgcn_s_barrier()
; #define PG8_SCHED __builtin_amdgcn_sched_barrier(0)
; template <class Epi, class Sched>
; __device__ __forceinline__ void gemm_phase(PG8_LAS unsigned char* lds, const Gemm g, const Sched& S, const Epi& E) {
;     ...
;             PG8_LDB(B0, 1, 0); PG8_SCHED; PG8_LDA(At, 1, 0); PG8_STAGE(PG8_SA(0, 1), a2 + hstep, voffA);
;             PG8_WAIT_L(8); PG8_BAR; PG8_WAIT_L(0); PG8_MMA(0, 0, At, B0); PG8_BAR; PG8_SCHED;
;             PG8_LDB(B1, 1, 1); PG8_STAGE(PG8_SB(1, 0), b3, voffB);
;             PG8_BAR; PG8_WAIT_L(0); PG8_MMA(0, 1, At, B1); PG8_BAR;
;             PG8_LDA(At, 1, 1); PG8_STAGE(PG8_SA(1, 0), a3, voffA);
;             PG8_BAR; PG8_WAIT_L(0); PG8_MMA(1, 0, At, B0); PG8_BAR; PG8_SCHED;
;             PG8_STAGE(PG8_SB(1, 1), b3 + hstepB, voffB);
;             PG8_WAIT_V(6); PG8_BAR; PG8_MMA(1, 1, At, B1); PG8_BAR;
	s_add_i32 s70, 0, 0x18000
	v_add_u32_e32 v140, s70, v195
	ds_read_b128 v[128:131], v140
	ds_read_b128 v[132:135], v140 offset:1024
	ds_read_b128 v[136:139], v140 offset:2048
	ds_read_b128 v[140:143], v140 offset:3072
	s_add_u32 s28, s38, 0x80000
	s_addc_u32 s29, s39, 0
	s_mov_b32 m0, s56
	ds_read_b128 v[144:147], v198 offset:32768
	ds_read_b128 v[148:151], v198 offset:33792
	ds_read_b128 v[152:155], v198 offset:34816
	ds_read_b128 v[156:159], v198 offset:35840
	ds_read_b128 v[160:163], v198 offset:36864
	ds_read_b128 v[180:183], v198 offset:37888
	ds_read_b128 v[184:187], v198 offset:38912
	ds_read_b128 v[188:191], v198 offset:39936
	global_load_lds_dwordx4 v166, s[28:29]
	s_mov_b32 m0, s57
	s_nop 0
	global_load_lds_dwordx4 v170, s[28:29]
	s_add_i32 s38, 0, 0x1c000
	s_add_u32 s28, s36, 0x8000
	s_addc_u32 s29, s37, 0
	s_add_i32 s39, s70, s54
	v_add_u32_e32 v212, s38, v195
	s_mov_b32 m0, s39
	ds_read_b128 v[200:203], v212
	ds_read_b128 v[204:207], v212 offset:1024
	ds_read_b128 v[208:211], v212 offset:2048
	ds_read_b128 v[212:215], v212 offset:3072
	s_waitcnt vmcnt(8)
	s_waitcnt lgkmcnt(0)
	s_barrier
	v_mfma_f32_16x16x32_bf16 v[124:127], v[128:131], v[144:147], v[124:127]
	v_mfma_f32_16x16x32_bf16 v[120:123], v[136:139], v[144:147], v[120:123]
	v_mfma_f32_16x16x32_bf16 v[116:119], v[128:131], v[152:155], v[116:119]
	v_mfma_f32_16x16x32_bf16 v[104:107], v[136:139], v[152:155], v[104:107]
	v_mfma_f32_16x16x32_bf16 v[92:95], v[128:131], v[160:163], v[92:95]
	v_mfma_f32_16x16x32_bf16 v[88:91], v[136:139], v[160:163], v[88:91]
	v_mfma_f32_16x16x32_bf16 v[76:79], v[128:131], v[184:187], v[76:79]
	v_mfma_f32_16x16x32_bf16 v[72:75], v[136:139], v[184:187], v[72:75]
	v_mfma_f32_16x16x32_bf16 v[124:127], v[132:135], v[148:151], v[124:127]
	v_mfma_f32_16x16x32_bf16 v[120:123], v[140:143], v[148:151], v[120:123]
	v_mfma_f32_16x16x32_bf16 v[116:119], v[132:135], v[156:159], v[116:119]
	v_mfma_f32_16x16x32_bf16 v[104:107], v[140:143], v[156:159], v[104:107]
	v_mfma_f32_16x16x32_bf16 v[92:95], v[132:135], v[180:183], v[92:95]
	v_mfma_f32_16x16x32_bf16 v[88:91], v[140:143], v[180:183], v[88:91]
	v_mfma_f32_16x16x32_bf16 v[76:79], v[132:135], v[188:191], v[76:79]
	v_mfma_f32_16x16x32_bf16 v[72:75], v[140:143], v[188:191], v[72:75]
	v_mfma_f32_16x16x32_bf16 v[112:115], v[200:203], v[144:147], v[112:115]
	v_mfma_f32_16x16x32_bf16 v[108:111], v[208:211], v[144:147], v[108:111]
	v_mfma_f32_16x16x32_bf16 v[100:103], v[200:203], v[152:155], v[100:103]
	v_mfma_f32_16x16x32_bf16 v[96:99], v[208:211], v[152:155], v[96:99]
	v_mfma_f32_16x16x32_bf16 v[84:87], v[200:203], v[160:163], v[84:87]
	v_mfma_f32_16x16x32_bf16 v[80:83], v[208:211], v[160:163], v[80:83]
	v_mfma_f32_16x16x32_bf16 v[68:71], v[200:203], v[184:187], v[68:71]
	v_mfma_f32_16x16x32_bf16 v[64:67], v[208:211], v[184:187], v[64:67]
	v_mfma_f32_16x16x32_bf16 v[112:115], v[204:207], v[148:151], v[112:115]
	v_mfma_f32_16x16x32_bf16 v[108:111], v[212:215], v[148:151], v[108:111]
	v_mfma_f32_16x16x32_bf16 v[100:103], v[204:207], v[156:159], v[100:103]
	v_mfma_f32_16x16x32_bf16 v[96:99], v[212:215], v[156:159], v[96:99]
	v_mfma_f32_16x16x32_bf16 v[84:87], v[204:207], v[180:183], v[84:87]
	v_mfma_f32_16x16x32_bf16 v[80:83], v[212:215], v[180:183], v[80:83]
	v_mfma_f32_16x16x32_bf16 v[68:71], v[204:207], v[188:191], v[68:71]
	v_mfma_f32_16x16x32_bf16 v[64:67], v[212:215], v[188:191], v[64:67]
	s_barrier
	global_load_lds_dwordx4 v164, s[28:29]
	s_add_i32 m0, s39, 0x2000
	s_nop 0
	global_load_lds_dwordx4 v168, s[28:29]
	s_mov_b32 m0, s59
	v_lshl_add_u64 v[192:193], v[192:193], 0, s[10:11]
	ds_read_b128 v[144:147], v198 offset:49152
	ds_read_b128 v[148:151], v198 offset:50176
	ds_read_b128 v[152:155], v198 offset:51200
	ds_read_b128 v[156:159], v198 offset:52224
	ds_read_b128 v[160:163], v198 offset:53248
	ds_read_b128 v[180:183], v198 offset:54272
	ds_read_b128 v[184:187], v198 offset:55296
	ds_read_b128 v[188:191], v198 offset:56320
	global_load_lds_dwordx4 v[192:193], off
	v_lshl_add_u64 v[192:193], v[216:217], 0, s[10:11]
	s_mov_b32 m0, s60
	s_nop 0
	global_load_lds_dwordx4 v[192:193], off
	s_add_u32 s28, s36, 0xc000
	s_addc_u32 s29, s37, 0
	s_add_i32 s36, s38, s54
	s_mov_b32 m0, s36
	s_nop 0
	global_load_lds_dwordx4 v164, s[28:29]
	s_add_i32 m0, s36, 0x2000
	s_nop 0
	global_load_lds_dwordx4 v168, s[28:29]
	s_add_i32 s69, s69, 2
	s_add_u32 s67, s67, 0x10000
	s_addc_u32 s68, s68, 0
	s_cmp_gt_u32 s69, 29
	s_mov_b64 s[28:29], s[30:31]
	s_waitcnt vmcnt(8)
	s_waitcnt lgkmcnt(0)
	s_barrier
	v_mfma_f32_16x16x32_bf16 v[60:63], v[128:131], v[144:147], v[60:63]
	v_mfma_f32_16x16x32_bf16 v[56:59], v[136:139], v[144:147], v[56:59]
	v_mfma_f32_16x16x32_bf16 v[44:47], v[128:131], v[152:155], v[44:47]
	v_mfma_f32_16x16x32_bf16 v[40:43], v[136:139], v[152:155], v[40:43]
	v_mfma_f32_16x16x32_bf16 v[28:31], v[128:131], v[160:163], v[28:31]
	v_mfma_f32_16x16x32_bf16 v[24:27], v[136:139], v[160:163], v[24:27]
	v_mfma_f32_16x16x32_bf16 v[12:15], v[128:131], v[184:187], v[12:15]
	v_mfma_f32_16x16x32_bf16 v[8:11], v[136:139], v[184:187], v[8:11]
	v_mfma_f32_16x16x32_bf16 v[60:63], v[132:135], v[148:151], v[60:63]
	v_mfma_f32_16x16x32_bf16 v[56:59], v[140:143], v[148:151], v[56:59]
	v_mfma_f32_16x16x32_bf16 v[44:47], v[132:135], v[156:159], v[44:47]
	v_mfma_f32_16x16x32_bf16 v[40:43], v[140:143], v[156:159], v[40:43]
	v_mfma_f32_16x16x32_bf16 v[28:31], v[132:135], v[180:183], v[28:31]
	v_mfma_f32_16x16x32_bf16 v[24:27], v[140:143], v[180:183], v[24:27]
	v_mfma_f32_16x16x32_bf16 v[12:15], v[132:135], v[188:191], v[12:15]
	v_mfma_f32_16x16x32_bf16 v[8:11], v[140:143], v[188:191], v[8:11]
	v_mfma_f32_16x16x32_bf16 v[52:55], v[200:203], v[144:147], v[52:55]
	v_mfma_f32_16x16x32_bf16 v[48:51], v[208:211], v[144:147], v[48:51]
	v_mfma_f32_16x16x32_bf16 v[36:39], v[200:203], v[152:155], v[36:39]
	v_mfma_f32_16x16x32_bf16 v[32:35], v[208:211], v[152:155], v[32:35]
	v_mfma_f32_16x16x32_bf16 v[20:23], v[200:203], v[160:163], v[20:23]
	v_mfma_f32_16x16x32_bf16 v[16:19], v[208:211], v[160:163], v[16:19]
	v_mfma_f32_16x16x32_bf16 v[4:7], v[200:203], v[184:187], v[4:7]
	v_mfma_f32_16x16x32_bf16 v[0:3], v[208:211], v[184:187], v[0:3]
	v_mfma_f32_16x16x32_bf16 v[52:55], v[204:207], v[148:151], v[52:55]
	v_mfma_f32_16x16x32_bf16 v[48:51], v[212:215], v[148:151], v[48:51]
	v_mfma_f32_16x16x32_bf16 v[36:39], v[204:207], v[156:159], v[36:39]
	v_mfma_f32_16x16x32_bf16 v[32:35], v[212:215], v[156:159], v[32:35]
	v_mfma_f32_16x16x32_bf16 v[20:23], v[204:207], v[180:183], v[20:23]
	v_mfma_f32_16x16x32_bf16 v[16:19], v[212:215], v[180:183], v[16:19]
	v_mfma_f32_16x16x32_bf16 v[4:7], v[204:207], v[188:191], v[4:7]
	v_mfma_f32_16x16x32_bf16 v[0:3], v[212:215], v[188:191], v[0:3]
	s_cbranch_scc1 .Lunit_exit_5
	s_barrier
	s_branch .LBB0_783

; #define PG8_STAGE(bufoff, gbase, voff) do { _Pragma("unroll") for (int _i = 0; _i < 2; ++_i) \
;         __builtin_amdgcn_global_load_lds((const unsigned*)((const char*)(gbase) + (voff)[_i]), (PG8_LAS unsigned*)(lds + (bufoff) + ldsw + _i * 8192), 16, 0, 0); } while (0)
; #define PG8_LDA(dst, b, h) do { _Pragma("unroll") for (int m = 0; m < 4; ++m) _Pragma("unroll") for (int k = 0; k < 2; ++k) dst[m][k] = *(const PG8_LAS bf16x8*)(lds + PG8_SA(b, h) + aoff + m * 2048 + k * 1024); } while (0)
; #define PG8_LDB(dst, b, h) do { _Pragma("unroll") for (int n = 0; n < 2; ++n) _Pragma("unroll") for (int k = 0; k < 2; ++k) dst[n][k] = *(const PG8_LAS bf16x8*)(lds + PG8_SB(b, h) + boff + n * 2048 + k * 1024); } while (0)
; #define PG8_MMA(ai, bj, At, Bt) do { __builtin_amdgcn_s_setprio(1); _Pragma("unroll") for (int m = 0; m < 4; ++m) _Pragma("unroll") for (int n = 0; n < 2; ++n) _Pragma("unroll") for (int k = 0; k < 2; ++k) \
;         acc[ai][bj][m][n] = __builtin_amdgcn_mfma_f32_16x16x32_bf16(Bt[n][k], At[m][k], acc[ai][bj][m][n], 0, 0, 0); __builtin_amdgcn_s_setprio(0); } while (0)
; #define PG8_WAIT_V(n) asm volatile("s_waitcnt vmcnt(" #n ")" ::: "memory")
; template <class Epi, class Sched>
; __device__ __forceinline__ void gemm_phase(PG8_LAS unsigned char* lds, const Gemm g, const Sched& S, const Epi& E) {
;     ...
;         for (int t = 0; t < nt; t += 2) {
;             const bool last = (t == nt - 2);
;             const char* a1 = cA + (size_t)(t + 1) * kstep;
;             const char* a2 = last ? nA : cA + (size_t)(t + 2) * kstep; const char* b2 = last ? nB : cB + (size_t)(t + 2) * kstepB;
;             const char* a3 = a2 + kstep; const char* b3 = b2 + kstepB;
;             if (last && has_next) S.a_ready(nxt);
;             PG8_LDB(B0, 0, 0); PG8_SCHED; PG8_LDA(At, 0, 0); PG8_STAGE(PG8_SA(1, 1), a1 + hstep, voffA);
;             PG8_WAIT_L(8); PG8_BAR; PG8_WAIT_L(0); PG8_MMA(0, 0, At, B0); PG8_BAR; PG8_SCHED;
;             PG8_LDB(B1, 0, 1); PG8_STAGE(PG8_SB(0, 0), b2, voffB);
;             PG8_BAR; PG8_WAIT_L(0); PG8_MMA(0, 1, At, B1); PG8_BAR;
;             PG8_LDA(At, 0, 1); PG8_STAGE(PG8_SA(0, 0), a2, voffA);
;             PG8_BAR; PG8_WAIT_L(0); PG8_MMA(1, 0, At, B0); PG8_BAR; PG8_SCHED;
;             PG8_STAGE(PG8_SB(0, 1), b2 + hstepB, voffB);
;             PG8_WAIT_V(6); PG8_BAR; PG8_MMA(1, 1, At, B1); PG8_BAR;
.Lhalf_skip_y_6:
.LBB0_904:
	ds_read_b128 v[152:155], v149
	ds_read_b128 v[156:159], v149 offset:1024
	ds_read_b128 v[160:163], v149 offset:2048
	ds_read_b128 v[164:167], v149 offset:3072
	s_add_u32 s22, s20, 0xfff80080
	s_addc_u32 s23, s21, -1
	s_cmp_eq_u32 s61, 28
	s_cselect_b32 s25, s11, s23
	s_cselect_b32 s24, s57, s22
	s_cselect_b32 s23, s13, s60
	s_cselect_b32 s22, s58, s59
	s_add_i32 m0, s19, 0xc000
	ds_read_b128 v[168:171], v150
	ds_read_b128 v[172:175], v150 offset:1024
	ds_read_b128 v[176:179], v150 offset:2048
	ds_read_b128 v[180:183], v150 offset:3072
	ds_read_b128 v[184:187], v150 offset:4096
	ds_read_b128 v[188:191], v150 offset:5120
	ds_read_b128 v[192:195], v150 offset:6144
	ds_read_b128 v[196:199], v150 offset:7168
	global_load_lds_dwordx4 v136, s[20:21]
	s_add_i32 m0, s19, 0xe000
	s_nop 0
	global_load_lds_dwordx4 v138, s[20:21]
	s_add_i32 s62, s53, s38
	s_mov_b32 m0, s62
	ds_read_b128 v[200:203], v151
	ds_read_b128 v[204:207], v151 offset:1024
	ds_read_b128 v[208:211], v151 offset:2048
	ds_read_b128 v[212:215], v151 offset:3072
	s_waitcnt vmcnt(8)
	s_waitcnt lgkmcnt(0)
	s_barrier
	v_mfma_f32_16x16x32_bf16 v[124:127], v[152:155], v[168:171], v[124:127]
	v_mfma_f32_16x16x32_bf16 v[120:123], v[160:163], v[168:171], v[120:123]
	v_mfma_f32_16x16x32_bf16 v[108:111], v[152:155], v[176:179], v[108:111]
	v_mfma_f32_16x16x32_bf16 v[104:107], v[160:163], v[176:179], v[104:107]
	v_mfma_f32_16x16x32_bf16 v[92:95], v[152:155], v[184:187], v[92:95]
	v_mfma_f32_16x16x32_bf16 v[88:91], v[160:163], v[184:187], v[88:91]
	v_mfma_f32_16x16x32_bf16 v[76:79], v[152:155], v[192:195], v[76:79]
	v_mfma_f32_16x16x32_bf16 v[72:75], v[160:163], v[192:195], v[72:75]
	v_mfma_f32_16x16x32_bf16 v[124:127], v[156:159], v[172:175], v[124:127]
	v_mfma_f32_16x16x32_bf16 v[120:123], v[164:167], v[172:175], v[120:123]
	v_mfma_f32_16x16x32_bf16 v[108:111], v[156:159], v[180:183], v[108:111]
	v_mfma_f32_16x16x32_bf16 v[104:107], v[164:167], v[180:183], v[104:107]
	v_mfma_f32_16x16x32_bf16 v[92:95], v[156:159], v[188:191], v[92:95]
	v_mfma_f32_16x16x32_bf16 v[88:91], v[164:167], v[188:191], v[88:91]
	v_mfma_f32_16x16x32_bf16 v[76:79], v[156:159], v[196:199], v[76:79]
	v_mfma_f32_16x16x32_bf16 v[72:75], v[164:167], v[196:199], v[72:75]
	v_mfma_f32_16x16x32_bf16 v[116:119], v[200:203], v[168:171], v[116:119]
	v_mfma_f32_16x16x32_bf16 v[112:115], v[208:211], v[168:171], v[112:115]
	v_mfma_f32_16x16x32_bf16 v[100:103], v[200:203], v[176:179], v[100:103]
	v_mfma_f32_16x16x32_bf16 v[96:99], v[208:211], v[176:179], v[96:99]
	v_mfma_f32_16x16x32_bf16 v[84:87], v[200:203], v[184:187], v[84:87]
	v_mfma_f32_16x16x32_bf16 v[80:83], v[208:211], v[184:187], v[80:83]
	v_mfma_f32_16x16x32_bf16 v[68:71], v[200:203], v[192:195], v[68:71]
	v_mfma_f32_16x16x32_bf16 v[64:67], v[208:211], v[192:195], v[64:67]
	v_mfma_f32_16x16x32_bf16 v[116:119], v[204:207], v[172:175], v[116:119]
	v_mfma_f32_16x16x32_bf16 v[112:115], v[212:215], v[172:175], v[112:115]
	v_mfma_f32_16x16x32_bf16 v[100:103], v[204:207], v[180:183], v[100:103]
	v_mfma_f32_16x16x32_bf16 v[96:99], v[212:215], v[180:183], v[96:99]
	v_mfma_f32_16x16x32_bf16 v[84:87], v[204:207], v[188:191], v[84:87]
	v_mfma_f32_16x16x32_bf16 v[80:83], v[212:215], v[188:191], v[80:83]
	v_mfma_f32_16x16x32_bf16 v[68:71], v[204:207], v[196:199], v[68:71]
	v_mfma_f32_16x16x32_bf16 v[64:67], v[212:215], v[196:199], v[64:67]
	s_barrier
	global_load_lds_dwordx4 v128, s[22:23]
	s_add_i32 m0, s62, 0x2000
	s_nop 0
	global_load_lds_dwordx4 v130, s[22:23]
	s_mov_b32 m0, s19
	v_lshl_add_u64 v[144:145], s[24:25], 0, v[134:135]
	ds_read_b128 v[168:171], v150 offset:16384
	ds_read_b128 v[172:175], v150 offset:17408
	ds_read_b128 v[176:179], v150 offset:18432
	ds_read_b128 v[180:183], v150 offset:19456
	ds_read_b128 v[184:187], v150 offset:20480
	ds_read_b128 v[188:191], v150 offset:21504
	ds_read_b128 v[192:195], v150 offset:22528
	ds_read_b128 v[196:199], v150 offset:23552
	global_load_lds_dwordx4 v[144:145], off
	v_lshl_add_u64 v[216:217], s[24:25], 0, v[132:133]
	s_mov_b32 m0, s46
	s_nop 0
	global_load_lds_dwordx4 v[216:217], off
	s_add_u32 s62, s22, 0x4000
	s_addc_u32 s63, s23, 0
	s_add_i32 s64, s54, s38
	s_mov_b32 m0, s64
	s_nop 0
	global_load_lds_dwordx4 v128, s[62:63]
	s_add_i32 m0, s64, 0x2000
	s_nop 0
	global_load_lds_dwordx4 v130, s[62:63]
	s_waitcnt vmcnt(8)
	s_waitcnt lgkmcnt(0)
	s_barrier
	v_mfma_f32_16x16x32_bf16 v[60:63], v[152:155], v[168:171], v[60:63]
	v_mfma_f32_16x16x32_bf16 v[56:59], v[160:163], v[168:171], v[56:59]
	v_mfma_f32_16x16x32_bf16 v[44:47], v[152:155], v[176:179], v[44:47]
	v_mfma_f32_16x16x32_bf16 v[40:43], v[160:163], v[176:179], v[40:43]
	v_mfma_f32_16x16x32_bf16 v[28:31], v[152:155], v[184:187], v[28:31]
	v_mfma_f32_16x16x32_bf16 v[24:27], v[160:163], v[184:187], v[24:27]
	v_mfma_f32_16x16x32_bf16 v[12:15], v[152:155], v[192:195], v[12:15]
	v_mfma_f32_16x16x32_bf16 v[8:11], v[160:163], v[192:195], v[8:11]
	v_mfma_f32_16x16x32_bf16 v[60:63], v[156:159], v[172:175], v[60:63]
	v_mfma_f32_16x16x32_bf16 v[56:59], v[164:167], v[172:175], v[56:59]
	v_mfma_f32_16x16x32_bf16 v[44:47], v[156:159], v[180:183], v[44:47]
	v_mfma_f32_16x16x32_bf16 v[40:43], v[164:167], v[180:183], v[40:43]
	v_mfma_f32_16x16x32_bf16 v[28:31], v[156:159], v[188:191], v[28:31]
	v_mfma_f32_16x16x32_bf16 v[24:27], v[164:167], v[188:191], v[24:27]
	v_mfma_f32_16x16x32_bf16 v[12:15], v[156:159], v[196:199], v[12:15]
	v_mfma_f32_16x16x32_bf16 v[8:11], v[164:167], v[196:199], v[8:11]
	v_mfma_f32_16x16x32_bf16 v[52:55], v[200:203], v[168:171], v[52:55]
	v_mfma_f32_16x16x32_bf16 v[48:51], v[208:211], v[168:171], v[48:51]
	v_mfma_f32_16x16x32_bf16 v[36:39], v[200:203], v[176:179], v[36:39]
	v_mfma_f32_16x16x32_bf16 v[32:35], v[208:211], v[176:179], v[32:35]
	v_mfma_f32_16x16x32_bf16 v[20:23], v[200:203], v[184:187], v[20:23]
	v_mfma_f32_16x16x32_bf16 v[16:19], v[208:211], v[184:187], v[16:19]
	v_mfma_f32_16x16x32_bf16 v[4:7], v[200:203], v[192:195], v[4:7]
	v_mfma_f32_16x16x32_bf16 v[0:3], v[208:211], v[192:195], v[0:3]
	v_mfma_f32_16x16x32_bf16 v[52:55], v[204:207], v[172:175], v[52:55]
	v_mfma_f32_16x16x32_bf16 v[48:51], v[212:215], v[172:175], v[48:51]
	v_mfma_f32_16x16x32_bf16 v[36:39], v[204:207], v[180:183], v[36:39]
	v_mfma_f32_16x16x32_bf16 v[32:35], v[212:215], v[180:183], v[32:35]
	v_mfma_f32_16x16x32_bf16 v[20:23], v[204:207], v[188:191], v[20:23]
	v_mfma_f32_16x16x32_bf16 v[16:19], v[212:215], v[188:191], v[16:19]
	v_mfma_f32_16x16x32_bf16 v[4:7], v[204:207], v[196:199], v[4:7]
	v_mfma_f32_16x16x32_bf16 v[0:3], v[212:215], v[196:199], v[0:3]
	s_barrier
; #define PG8_STAGE(bufoff, gbase, voff) do { _Pragma("unroll") for (int _i = 0; _i < 2; ++_i) \
;         __builtin_amdgcn_global_load_lds((const unsigned*)((const char*)(gbase) + (voff)[_i]), (PG8_LAS unsigned*)(lds + (bufoff) + ldsw + _i * 8192), 16, 0, 0); } while (0)
; #define PG8_LDA(dst, b, h) do { _Pragma("unroll") for (int m = 0; m < 4; ++m) _Pragma("unroll") for (int k = 0; k < 2; ++k) dst[m][k] = *(const PG8_LAS bf16x8*)(lds + PG8_SA(b, h) + aoff + m * 2048 + k * 1024); } while (0)
; #define PG8_LDB(dst, b, h) do { _Pragma("unroll") for (int n = 0; n < 2; ++n) _Pragma("unroll") for (int k = 0; k < 2; ++k) dst[n][k] = *(const PG8_LAS bf16x8*)(lds + PG8_SB(b, h) + boff + n * 2048 + k * 1024); } while (0)
; #define PG8_MMA(ai, bj, At, Bt) do { __builtin_amdgcn_s_setprio(1); _Pragma("unroll") for (int m = 0; m < 4; ++m) _Pragma("unroll") for (int n = 0; n < 2; ++n) _Pragma("unroll") for (int k = 0; k < 2; ++k) \
;         acc[ai][bj][m][n] = __builtin_amdgcn_mfma_f32_16x16x32_bf16(Bt[n][k], At[m][k], acc[ai][bj][m][n], 0, 0, 0); __builtin_amdgcn_s_setprio(0); } while (0)
; #define PG8_WAIT_V(n) asm volatile("s_waitcnt vmcnt(" #n ")" ::: "memory")
; #define PG8_WAIT_L(n) asm volatile("s_waitcnt lgkmcnt(" #n ")" ::: "memory")
; #define PG8_BAR __builtin_amdgcn_s_barrier()
; #define PG8_SCHED __builtin_amdgcn_sched_barrier(0)
; template <class Epi, class Sched>
; __device__ __forceinline__ void gemm_phase(PG8_LAS unsigned char* lds, const Gemm g, const Sched& S, const Epi& E) {
;     ...
;             PG8_LDB(B0, 1, 0); PG8_SCHED; PG8_LDA(At, 1, 0); PG8_STAGE(PG8_SA(0, 1), a2 + hstep, voffA);
;             PG8_WAIT_L(8); PG8_BAR; PG8_WAIT_L(0); PG8_MMA(0, 0, At, B0); PG8_BAR; PG8_SCHED;
;             PG8_LDB(B1, 1, 1); PG8_STAGE(PG8_SB(1, 0), b3, voffB);
;             PG8_BAR; PG8_WAIT_L(0); PG8_MMA(0, 1, At, B1); PG8_BAR;
;             PG8_LDA(At, 1, 1); PG8_STAGE(PG8_SA(1, 0), a3, voffA);
;             PG8_BAR; PG8_WAIT_L(0); PG8_MMA(1, 0, At, B0); PG8_BAR; PG8_SCHED;
;             PG8_STAGE(PG8_SB(1, 1), b3 + hstepB, voffB);
;             PG8_WAIT_V(6); PG8_BAR; PG8_MMA(1, 1, At, B1); PG8_BAR;
	s_add_i32 s62, 0, 0x18000
	v_add_u32_e32 v164, s62, v147
	ds_read_b128 v[152:155], v164
	ds_read_b128 v[156:159], v164 offset:1024
	ds_read_b128 v[160:163], v164 offset:2048
	ds_read_b128 v[164:167], v164 offset:3072
	s_add_u32 s24, s24, 0x80000
	s_addc_u32 s25, s25, 0
	s_mov_b32 m0, s47
	ds_read_b128 v[168:171], v150 offset:32768
	ds_read_b128 v[172:175], v150 offset:33792
	ds_read_b128 v[176:179], v150 offset:34816
	ds_read_b128 v[180:183], v150 offset:35840
	ds_read_b128 v[184:187], v150 offset:36864
	ds_read_b128 v[188:191], v150 offset:37888
	ds_read_b128 v[192:195], v150 offset:38912
	ds_read_b128 v[196:199], v150 offset:39936
	global_load_lds_dwordx4 v134, s[24:25]
	s_mov_b32 m0, s48
	s_nop 0
	global_load_lds_dwordx4 v132, s[24:25]
	s_add_i32 s63, 0, 0x1c000
	s_add_u32 s24, s22, 0x8000
	s_addc_u32 s25, s23, 0
	s_add_i32 s62, s62, s38
	v_add_u32_e32 v212, s63, v147
	s_mov_b32 m0, s62
	ds_read_b128 v[200:203], v212
	ds_read_b128 v[204:207], v212 offset:1024
	ds_read_b128 v[208:211], v212 offset:2048
	ds_read_b128 v[212:215], v212 offset:3072
	s_waitcnt vmcnt(8)
	s_waitcnt lgkmcnt(0)
	s_barrier
	v_mfma_f32_16x16x32_bf16 v[124:127], v[152:155], v[168:171], v[124:127]
	v_mfma_f32_16x16x32_bf16 v[120:123], v[160:163], v[168:171], v[120:123]
	v_mfma_f32_16x16x32_bf16 v[108:111], v[152:155], v[176:179], v[108:111]
	v_mfma_f32_16x16x32_bf16 v[104:107], v[160:163], v[176:179], v[104:107]
	v_mfma_f32_16x16x32_bf16 v[92:95], v[152:155], v[184:187], v[92:95]
	v_mfma_f32_16x16x32_bf16 v[88:91], v[160:163], v[184:187], v[88:91]
	v_mfma_f32_16x16x32_bf16 v[76:79], v[152:155], v[192:195], v[76:79]
	v_mfma_f32_16x16x32_bf16 v[72:75], v[160:163], v[192:195], v[72:75]
	v_mfma_f32_16x16x32_bf16 v[124:127], v[156:159], v[172:175], v[124:127]
	v_mfma_f32_16x16x32_bf16 v[120:123], v[164:167], v[172:175], v[120:123]
	v_mfma_f32_16x16x32_bf16 v[108:111], v[156:159], v[180:183], v[108:111]
	v_mfma_f32_16x16x32_bf16 v[104:107], v[164:167], v[180:183], v[104:107]
	v_mfma_f32_16x16x32_bf16 v[92:95], v[156:159], v[188:191], v[92:95]
	v_mfma_f32_16x16x32_bf16 v[88:91], v[164:167], v[188:191], v[88:91]
	v_mfma_f32_16x16x32_bf16 v[76:79], v[156:159], v[196:199], v[76:79]
	v_mfma_f32_16x16x32_bf16 v[72:75], v[164:167], v[196:199], v[72:75]
	v_mfma_f32_16x16x32_bf16 v[116:119], v[200:203], v[168:171], v[116:119]
	v_mfma_f32_16x16x32_bf16 v[112:115], v[208:211], v[168:171], v[112:115]
	v_mfma_f32_16x16x32_bf16 v[100:103], v[200:203], v[176:179], v[100:103]
	v_mfma_f32_16x16x32_bf16 v[96:99], v[208:211], v[176:179], v[96:99]
	v_mfma_f32_16x16x32_bf16 v[84:87], v[200:203], v[184:187], v[84:87]
	v_mfma_f32_16x16x32_bf16 v[80:83], v[208:211], v[184:187], v[80:83]
	v_mfma_f32_16x16x32_bf16 v[68:71], v[200:203], v[192:195], v[68:71]
	v_mfma_f32_16x16x32_bf16 v[64:67], v[208:211], v[192:195], v[64:67]
	v_mfma_f32_16x16x32_bf16 v[116:119], v[204:207], v[172:175], v[116:119]
	v_mfma_f32_16x16x32_bf16 v[112:115], v[212:215], v[172:175], v[112:115]
	v_mfma_f32_16x16x32_bf16 v[100:103], v[204:207], v[180:183], v[100:103]
	v_mfma_f32_16x16x32_bf16 v[96:99], v[212:215], v[180:183], v[96:99]
	v_mfma_f32_16x16x32_bf16 v[84:87], v[204:207], v[188:191], v[84:87]
	v_mfma_f32_16x16x32_bf16 v[80:83], v[212:215], v[188:191], v[80:83]
	v_mfma_f32_16x16x32_bf16 v[68:71], v[204:207], v[196:199], v[68:71]
	v_mfma_f32_16x16x32_bf16 v[64:67], v[212:215], v[196:199], v[64:67]
	s_barrier
	global_load_lds_dwordx4 v128, s[24:25]
	s_add_i32 m0, s62, 0x2000
	s_nop 0
	global_load_lds_dwordx4 v130, s[24:25]
	s_mov_b32 m0, s50
	v_lshl_add_u64 v[144:145], v[144:145], 0, s[8:9]
	ds_read_b128 v[168:171], v150 offset:49152
	ds_read_b128 v[172:175], v150 offset:50176
	ds_read_b128 v[176:179], v150 offset:51200
	ds_read_b128 v[180:183], v150 offset:52224
	ds_read_b128 v[184:187], v150 offset:53248
	ds_read_b128 v[188:191], v150 offset:54272
	ds_read_b128 v[192:195], v150 offset:55296
	ds_read_b128 v[196:199], v150 offset:56320
	global_load_lds_dwordx4 v[144:145], off
	v_lshl_add_u64 v[144:145], v[216:217], 0, s[8:9]
	s_mov_b32 m0, s51
	s_nop 0
	global_load_lds_dwordx4 v[144:145], off
	s_add_u32 s22, s22, 0xc000
	s_addc_u32 s23, s23, 0
	s_add_i32 s24, s63, s38
	s_mov_b32 m0, s24
	s_nop 0
	global_load_lds_dwordx4 v128, s[22:23]
	s_add_i32 m0, s24, 0x2000
	s_nop 0
	global_load_lds_dwordx4 v130, s[22:23]
	s_add_i32 s61, s61, 2
	s_add_u32 s59, s59, 0x10000
	s_addc_u32 s60, s60, 0
	s_add_u32 s20, s20, 0x100
	s_addc_u32 s21, s21, 0
	s_cmp_gt_u32 s61, 29
	s_waitcnt vmcnt(8)
	s_waitcnt lgkmcnt(0)
	s_barrier
	v_mfma_f32_16x16x32_bf16 v[60:63], v[152:155], v[168:171], v[60:63]
	v_mfma_f32_16x16x32_bf16 v[56:59], v[160:163], v[168:171], v[56:59]
	v_mfma_f32_16x16x32_bf16 v[44:47], v[152:155], v[176:179], v[44:47]
	v_mfma_f32_16x16x32_bf16 v[40:43], v[160:163], v[176:179], v[40:43]
	v_mfma_f32_16x16x32_bf16 v[28:31], v[152:155], v[184:187], v[28:31]
	v_mfma_f32_16x16x32_bf16 v[24:27], v[160:163], v[184:187], v[24:27]
	v_mfma_f32_16x16x32_bf16 v[12:15], v[152:155], v[192:195], v[12:15]
	v_mfma_f32_16x16x32_bf16 v[8:11], v[160:163], v[192:195], v[8:11]
	v_mfma_f32_16x16x32_bf16 v[60:63], v[156:159], v[172:175], v[60:63]
	v_mfma_f32_16x16x32_bf16 v[56:59], v[164:167], v[172:175], v[56:59]
	v_mfma_f32_16x16x32_bf16 v[44:47], v[156:159], v[180:183], v[44:47]
	v_mfma_f32_16x16x32_bf16 v[40:43], v[164:167], v[180:183], v[40:43]
	v_mfma_f32_16x16x32_bf16 v[28:31], v[156:159], v[188:191], v[28:31]
	v_mfma_f32_16x16x32_bf16 v[24:27], v[164:167], v[188:191], v[24:27]
	v_mfma_f32_16x16x32_bf16 v[12:15], v[156:159], v[196:199], v[12:15]
	v_mfma_f32_16x16x32_bf16 v[8:11], v[164:167], v[196:199], v[8:11]
	v_mfma_f32_16x16x32_bf16 v[52:55], v[200:203], v[168:171], v[52:55]
	v_mfma_f32_16x16x32_bf16 v[48:51], v[208:211], v[168:171], v[48:51]
	v_mfma_f32_16x16x32_bf16 v[36:39], v[200:203], v[176:179], v[36:39]
	v_mfma_f32_16x16x32_bf16 v[32:35], v[208:211], v[176:179], v[32:35]
	v_mfma_f32_16x16x32_bf16 v[20:23], v[200:203], v[184:187], v[20:23]
	v_mfma_f32_16x16x32_bf16 v[16:19], v[208:211], v[184:187], v[16:19]
	v_mfma_f32_16x16x32_bf16 v[4:7], v[200:203], v[192:195], v[4:7]
	v_mfma_f32_16x16x32_bf16 v[0:3], v[208:211], v[192:195], v[0:3]
	v_mfma_f32_16x16x32_bf16 v[52:55], v[204:207], v[172:175], v[52:55]
	v_mfma_f32_16x16x32_bf16 v[48:51], v[212:215], v[172:175], v[48:51]
	v_mfma_f32_16x16x32_bf16 v[36:39], v[204:207], v[180:183], v[36:39]
	v_mfma_f32_16x16x32_bf16 v[32:35], v[212:215], v[180:183], v[32:35]
	v_mfma_f32_16x16x32_bf16 v[20:23], v[204:207], v[188:191], v[20:23]
	v_mfma_f32_16x16x32_bf16 v[16:19], v[212:215], v[188:191], v[16:19]
	v_mfma_f32_16x16x32_bf16 v[4:7], v[204:207], v[196:199], v[4:7]
	v_mfma_f32_16x16x32_bf16 v[0:3], v[212:215], v[196:199], v[0:3]
	s_cbranch_scc1 .Lunit_exit_6
	s_barrier
	s_branch .LBB0_904

; #define PG8_STAGE(bufoff, gbase, voff) do { _Pragma("unroll") for (int _i = 0; _i < 2; ++_i) \
;         __builtin_amdgcn_global_load_lds((const unsigned*)((const char*)(gbase) + (voff)[_i]), (PG8_LAS unsigned*)(lds + (bufoff) + ldsw + _i * 8192), 16, 0, 0); } while (0)
; #define PG8_LDA(dst, b, h) do { _Pragma("unroll") for (int m = 0; m < 4; ++m) _Pragma("unroll") for (int k = 0; k < 2; ++k) dst[m][k] = *(const PG8_LAS bf16x8*)(lds + PG8_SA(b, h) + aoff + m * 2048 + k * 1024); } while (0)
; #define PG8_LDB(dst, b, h) do { _Pragma("unroll") for (int n = 0; n < 2; ++n) _Pragma("unroll") for (int k = 0; k < 2; ++k) dst[n][k] = *(const PG8_LAS bf16x8*)(lds + PG8_SB(b, h) + boff + n * 2048 + k * 1024); } while (0)
; #define PG8_MMA(ai, bj, At, Bt) do { __builtin_amdgcn_s_setprio(1); _Pragma("unroll") for (int m = 0; m < 4; ++m) _Pragma("unroll") for (int n = 0; n < 2; ++n) _Pragma("unroll") for (int k = 0; k < 2; ++k) \
;         acc[ai][bj][m][n] = __builtin_amdgcn_mfma_f32_16x16x32_bf16(Bt[n][k], At[m][k], acc[ai][bj][m][n], 0, 0, 0); __builtin_amdgcn_s_setprio(0); } while (0)
; #define PG8_WAIT_V(n) asm volatile("s_waitcnt vmcnt(" #n ")" ::: "memory")
; template <class Epi, class Sched>
; __device__ __forceinline__ void gemm_phase(PG8_LAS unsigned char* lds, const Gemm g, const Sched& S, const Epi& E) {
;     ...
;         for (int t = 0; t < nt; t += 2) {
;             const bool last = (t == nt - 2);
;             const char* a1 = cA + (size_t)(t + 1) * kstep;
;             const char* a2 = last ? nA : cA + (size_t)(t + 2) * kstep; const char* b2 = last ? nB : cB + (size_t)(t + 2) * kstepB;
;             const char* a3 = a2 + kstep; const char* b3 = b2 + kstepB;
;             if (last && has_next) S.a_ready(nxt);
;             PG8_LDB(B0, 0, 0); PG8_SCHED; PG8_LDA(At, 0, 0); PG8_STAGE(PG8_SA(1, 1), a1 + hstep, voffA);
;             PG8_WAIT_L(8); PG8_BAR; PG8_WAIT_L(0); PG8_MMA(0, 0, At, B0); PG8_BAR; PG8_SCHED;
;             PG8_LDB(B1, 0, 1); PG8_STAGE(PG8_SB(0, 0), b2, voffB);
;             PG8_BAR; PG8_WAIT_L(0); PG8_MMA(0, 1, At, B1); PG8_BAR;
;             PG8_LDA(At, 0, 1); PG8_STAGE(PG8_SA(0, 0), a2, voffA);
;             PG8_BAR; PG8_WAIT_L(0); PG8_MMA(1, 0, At, B0); PG8_BAR; PG8_SCHED;
;             PG8_STAGE(PG8_SB(0, 1), b2 + hstepB, voffB);
;             PG8_WAIT_V(6); PG8_BAR; PG8_MMA(1, 1, At, B1); PG8_BAR;
.Lhalf_skip_y_7:
.LBB0_980:
	ds_read_b128 v[128:131], v197
	ds_read_b128 v[132:135], v197 offset:1024
	ds_read_b128 v[136:139], v197 offset:2048
	ds_read_b128 v[140:143], v197 offset:3072
	s_add_u32 s24, s22, 0x100
	s_addc_u32 s25, s23, 0
	s_cmpk_eq_i32 s65, 0x52
	s_cselect_b32 s29, s7, s25
	s_cselect_b32 s28, s6, s24
	s_cselect_b32 s27, s9, s64
	s_cselect_b32 s26, s8, s63
	v_lshl_add_u64 v[192:193], s[22:23], 0, v[172:173]
	s_add_i32 m0, s49, 0xc000
	ds_read_b128 v[144:147], v198
	ds_read_b128 v[148:151], v198 offset:1024
	ds_read_b128 v[152:155], v198 offset:2048
	ds_read_b128 v[156:159], v198 offset:3072
	ds_read_b128 v[160:163], v198 offset:4096
	ds_read_b128 v[180:183], v198 offset:5120
	ds_read_b128 v[184:187], v198 offset:6144
	ds_read_b128 v[188:191], v198 offset:7168
	global_load_lds_dwordx4 v[192:193], off
	v_lshl_add_u64 v[192:193], s[22:23], 0, v[174:175]
	s_add_i32 m0, s49, 0xe000
	s_nop 0
	global_load_lds_dwordx4 v[192:193], off
	s_add_i32 s22, s57, s48
	s_mov_b32 m0, s22
	ds_read_b128 v[200:203], v199
	ds_read_b128 v[204:207], v199 offset:1024
	ds_read_b128 v[208:211], v199 offset:2048
	ds_read_b128 v[212:215], v199 offset:3072
	s_waitcnt vmcnt(8)
	s_waitcnt lgkmcnt(0)
	s_barrier
	v_mfma_f32_16x16x32_bf16 v[124:127], v[128:131], v[144:147], v[124:127]
	v_mfma_f32_16x16x32_bf16 v[120:123], v[136:139], v[144:147], v[120:123]
	v_mfma_f32_16x16x32_bf16 v[116:119], v[128:131], v[152:155], v[116:119]
	v_mfma_f32_16x16x32_bf16 v[104:107], v[136:139], v[152:155], v[104:107]
	v_mfma_f32_16x16x32_bf16 v[92:95], v[128:131], v[160:163], v[92:95]
	v_mfma_f32_16x16x32_bf16 v[88:91], v[136:139], v[160:163], v[88:91]
	v_mfma_f32_16x16x32_bf16 v[76:79], v[128:131], v[184:187], v[76:79]
	v_mfma_f32_16x16x32_bf16 v[72:75], v[136:139], v[184:187], v[72:75]
	v_mfma_f32_16x16x32_bf16 v[124:127], v[132:135], v[148:151], v[124:127]
	v_mfma_f32_16x16x32_bf16 v[120:123], v[140:143], v[148:151], v[120:123]
	v_mfma_f32_16x16x32_bf16 v[116:119], v[132:135], v[156:159], v[116:119]
	v_mfma_f32_16x16x32_bf16 v[104:107], v[140:143], v[156:159], v[104:107]
	v_mfma_f32_16x16x32_bf16 v[92:95], v[132:135], v[180:183], v[92:95]
	v_mfma_f32_16x16x32_bf16 v[88:91], v[140:143], v[180:183], v[88:91]
	v_mfma_f32_16x16x32_bf16 v[76:79], v[132:135], v[188:191], v[76:79]
	v_mfma_f32_16x16x32_bf16 v[72:75], v[140:143], v[188:191], v[72:75]
	v_mfma_f32_16x16x32_bf16 v[112:115], v[200:203], v[144:147], v[112:115]
	v_mfma_f32_16x16x32_bf16 v[108:111], v[208:211], v[144:147], v[108:111]
	v_mfma_f32_16x16x32_bf16 v[100:103], v[200:203], v[152:155], v[100:103]
	v_mfma_f32_16x16x32_bf16 v[96:99], v[208:211], v[152:155], v[96:99]
	v_mfma_f32_16x16x32_bf16 v[84:87], v[200:203], v[160:163], v[84:87]
	v_mfma_f32_16x16x32_bf16 v[80:83], v[208:211], v[160:163], v[80:83]
	v_mfma_f32_16x16x32_bf16 v[68:71], v[200:203], v[184:187], v[68:71]
	v_mfma_f32_16x16x32_bf16 v[64:67], v[208:211], v[184:187], v[64:67]
	v_mfma_f32_16x16x32_bf16 v[112:115], v[204:207], v[148:151], v[112:115]
	v_mfma_f32_16x16x32_bf16 v[108:111], v[212:215], v[148:151], v[108:111]
	v_mfma_f32_16x16x32_bf16 v[100:103], v[204:207], v[156:159], v[100:103]
	v_mfma_f32_16x16x32_bf16 v[96:99], v[212:215], v[156:159], v[96:99]
	v_mfma_f32_16x16x32_bf16 v[84:87], v[204:207], v[180:183], v[84:87]
	v_mfma_f32_16x16x32_bf16 v[80:83], v[212:215], v[180:183], v[80:83]
	v_mfma_f32_16x16x32_bf16 v[68:71], v[204:207], v[188:191], v[68:71]
	v_mfma_f32_16x16x32_bf16 v[64:67], v[212:215], v[188:191], v[64:67]
	s_barrier
	global_load_lds_dwordx4 v164, s[26:27]
	s_add_i32 m0, s22, 0x2000
	s_nop 0
	global_load_lds_dwordx4 v168, s[26:27]
	s_mov_b32 m0, s49
	v_lshl_add_u64 v[192:193], s[28:29], 0, v[166:167]
	ds_read_b128 v[144:147], v198 offset:16384
	ds_read_b128 v[148:151], v198 offset:17408
	ds_read_b128 v[152:155], v198 offset:18432
	ds_read_b128 v[156:159], v198 offset:19456
	ds_read_b128 v[160:163], v198 offset:20480
	ds_read_b128 v[180:183], v198 offset:21504
	ds_read_b128 v[184:187], v198 offset:22528
	ds_read_b128 v[188:191], v198 offset:23552
	global_load_lds_dwordx4 v[192:193], off
	v_lshl_add_u64 v[216:217], s[28:29], 0, v[170:171]
	s_mov_b32 m0, s50
	s_nop 0
	global_load_lds_dwordx4 v[216:217], off
	s_add_u32 s22, s26, 0x4000
	s_addc_u32 s23, s27, 0
	s_add_i32 s66, s58, s48
	s_mov_b32 m0, s66
	s_nop 0
	global_load_lds_dwordx4 v164, s[22:23]
	s_add_i32 m0, s66, 0x2000
	s_nop 0
	global_load_lds_dwordx4 v168, s[22:23]
	s_waitcnt vmcnt(8)
	s_waitcnt lgkmcnt(0)
	s_barrier
	v_mfma_f32_16x16x32_bf16 v[60:63], v[128:131], v[144:147], v[60:63]
	v_mfma_f32_16x16x32_bf16 v[56:59], v[136:139], v[144:147], v[56:59]
	v_mfma_f32_16x16x32_bf16 v[44:47], v[128:131], v[152:155], v[44:47]
	v_mfma_f32_16x16x32_bf16 v[40:43], v[136:139], v[152:155], v[40:43]
	v_mfma_f32_16x16x32_bf16 v[28:31], v[128:131], v[160:163], v[28:31]
	v_mfma_f32_16x16x32_bf16 v[24:27], v[136:139], v[160:163], v[24:27]
	v_mfma_f32_16x16x32_bf16 v[12:15], v[128:131], v[184:187], v[12:15]
	v_mfma_f32_16x16x32_bf16 v[8:11], v[136:139], v[184:187], v[8:11]
	v_mfma_f32_16x16x32_bf16 v[60:63], v[132:135], v[148:151], v[60:63]
	v_mfma_f32_16x16x32_bf16 v[56:59], v[140:143], v[148:151], v[56:59]
	v_mfma_f32_16x16x32_bf16 v[44:47], v[132:135], v[156:159], v[44:47]
	v_mfma_f32_16x16x32_bf16 v[40:43], v[140:143], v[156:159], v[40:43]
	v_mfma_f32_16x16x32_bf16 v[28:31], v[132:135], v[180:183], v[28:31]
	v_mfma_f32_16x16x32_bf16 v[24:27], v[140:143], v[180:183], v[24:27]
	v_mfma_f32_16x16x32_bf16 v[12:15], v[132:135], v[188:191], v[12:15]
	v_mfma_f32_16x16x32_bf16 v[8:11], v[140:143], v[188:191], v[8:11]
	v_mfma_f32_16x16x32_bf16 v[52:55], v[200:203], v[144:147], v[52:55]
	v_mfma_f32_16x16x32_bf16 v[48:51], v[208:211], v[144:147], v[48:51]
	v_mfma_f32_16x16x32_bf16 v[36:39], v[200:203], v[152:155], v[36:39]
	v_mfma_f32_16x16x32_bf16 v[32:35], v[208:211], v[152:155], v[32:35]
	v_mfma_f32_16x16x32_bf16 v[20:23], v[200:203], v[160:163], v[20:23]
	v_mfma_f32_16x16x32_bf16 v[16:19], v[208:211], v[160:163], v[16:19]
	v_mfma_f32_16x16x32_bf16 v[4:7], v[200:203], v[184:187], v[4:7]
	v_mfma_f32_16x16x32_bf16 v[0:3], v[208:211], v[184:187], v[0:3]
	v_mfma_f32_16x16x32_bf16 v[52:55], v[204:207], v[148:151], v[52:55]
	v_mfma_f32_16x16x32_bf16 v[48:51], v[212:215], v[148:151], v[48:51]
	v_mfma_f32_16x16x32_bf16 v[36:39], v[204:207], v[156:159], v[36:39]
	v_mfma_f32_16x16x32_bf16 v[32:35], v[212:215], v[156:159], v[32:35]
	v_mfma_f32_16x16x32_bf16 v[20:23], v[204:207], v[180:183], v[20:23]
	v_mfma_f32_16x16x32_bf16 v[16:19], v[212:215], v[180:183], v[16:19]
	v_mfma_f32_16x16x32_bf16 v[4:7], v[204:207], v[188:191], v[4:7]
	v_mfma_f32_16x16x32_bf16 v[0:3], v[212:215], v[188:191], v[0:3]
	s_barrier
; #define PG8_STAGE(bufoff, gbase, voff) do { _Pragma("unroll") for (int _i = 0; _i < 2; ++_i) \
;         __builtin_amdgcn_global_load_lds((const unsigned*)((const char*)(gbase) + (voff)[_i]), (PG8_LAS unsigned*)(lds + (bufoff) + ldsw + _i * 8192), 16, 0, 0); } while (0)
; #define PG8_LDA(dst, b, h) do { _Pragma("unroll") for (int m = 0; m < 4; ++m) _Pragma("unroll") for (int k = 0; k < 2; ++k) dst[m][k] = *(const PG8_LAS bf16x8*)(lds + PG8_SA(b, h) + aoff + m * 2048 + k * 1024); } while (0)
; #define PG8_LDB(dst, b, h) do { _Pragma("unroll") for (int n = 0; n < 2; ++n) _Pragma("unroll") for (int k = 0; k < 2; ++k) dst[n][k] = *(const PG8_LAS bf16x8*)(lds + PG8_SB(b, h) + boff + n * 2048 + k * 1024); } while (0)
; #define PG8_MMA(ai, bj, At, Bt) do { __builtin_amdgcn_s_setprio(1); _Pragma("unroll") for (int m = 0; m < 4; ++m) _Pragma("unroll") for (int n = 0; n < 2; ++n) _Pragma("unroll") for (int k = 0; k < 2; ++k) \
;         acc[ai][bj][m][n] = __builtin_amdgcn_mfma_f32_16x16x32_bf16(Bt[n][k], At[m][k], acc[ai][bj][m][n], 0, 0, 0); __builtin_amdgcn_s_setprio(0); } while (0)
; #define PG8_WAIT_V(n) asm volatile("s_waitcnt vmcnt(" #n ")" ::: "memory")
; #define PG8_WAIT_L(n) asm volatile("s_waitcnt lgkmcnt(" #n ")" ::: "memory")
; #define PG8_BAR __builtin_amdgcn_s_barrier()
; #define PG8_SCHED __builtin_amdgcn_sched_barrier(0)
; template <class Epi, class Sched>
; __device__ __forceinline__ void gemm_phase(PG8_LAS unsigned char* lds, const Gemm g, const Sched& S, const Epi& E) {
;     ...
;             PG8_LDB(B0, 1, 0); PG8_SCHED; PG8_LDA(At, 1, 0); PG8_STAGE(PG8_SA(0, 1), a2 + hstep, voffA);
;             PG8_WAIT_L(8); PG8_BAR; PG8_WAIT_L(0); PG8_MMA(0, 0, At, B0); PG8_BAR; PG8_SCHED;
;             PG8_LDB(B1, 1, 1); PG8_STAGE(PG8_SB(1, 0), b3, voffB);
;             PG8_BAR; PG8_WAIT_L(0); PG8_MMA(0, 1, At, B1); PG8_BAR;
;             PG8_LDA(At, 1, 1); PG8_STAGE(PG8_SA(1, 0), a3, voffA);
;             PG8_BAR; PG8_WAIT_L(0); PG8_MMA(1, 0, At, B0); PG8_BAR; PG8_SCHED;
;             PG8_STAGE(PG8_SB(1, 1), b3 + hstepB, voffB);
;             PG8_WAIT_V(6); PG8_BAR; PG8_MMA(1, 1, At, B1); PG8_BAR;
	s_add_i32 s66, 0, 0x18000
	v_add_u32_e32 v140, s66, v195
	ds_read_b128 v[128:131], v140
	ds_read_b128 v[132:135], v140 offset:1024
	ds_read_b128 v[136:139], v140 offset:2048
	ds_read_b128 v[140:143], v140 offset:3072
	s_add_u32 s22, s28, 0x158000
	s_addc_u32 s23, s29, 0
	s_mov_b32 m0, s51
	ds_read_b128 v[144:147], v198 offset:32768
	ds_read_b128 v[148:151], v198 offset:33792
	ds_read_b128 v[152:155], v198 offset:34816
	ds_read_b128 v[156:159], v198 offset:35840
	ds_read_b128 v[160:163], v198 offset:36864
	ds_read_b128 v[180:183], v198 offset:37888
	ds_read_b128 v[184:187], v198 offset:38912
	ds_read_b128 v[188:191], v198 offset:39936
	global_load_lds_dwordx4 v166, s[22:23]
	s_mov_b32 m0, s52
	s_nop 0
	global_load_lds_dwordx4 v170, s[22:23]
	s_add_i32 s28, 0, 0x1c000
	s_add_u32 s22, s26, 0x8000
	s_addc_u32 s23, s27, 0
	s_add_i32 s29, s66, s48
	v_add_u32_e32 v212, s28, v195
	s_mov_b32 m0, s29
	ds_read_b128 v[200:203], v212
	ds_read_b128 v[204:207], v212 offset:1024
	ds_read_b128 v[208:211], v212 offset:2048
	ds_read_b128 v[212:215], v212 offset:3072
	s_waitcnt vmcnt(8)
	s_waitcnt lgkmcnt(0)
	s_barrier
	v_mfma_f32_16x16x32_bf16 v[124:127], v[128:131], v[144:147], v[124:127]
	v_mfma_f32_16x16x32_bf16 v[120:123], v[136:139], v[144:147], v[120:123]
	v_mfma_f32_16x16x32_bf16 v[116:119], v[128:131], v[152:155], v[116:119]
	v_mfma_f32_16x16x32_bf16 v[104:107], v[136:139], v[152:155], v[104:107]
	v_mfma_f32_16x16x32_bf16 v[92:95], v[128:131], v[160:163], v[92:95]
	v_mfma_f32_16x16x32_bf16 v[88:91], v[136:139], v[160:163], v[88:91]
	v_mfma_f32_16x16x32_bf16 v[76:79], v[128:131], v[184:187], v[76:79]
	v_mfma_f32_16x16x32_bf16 v[72:75], v[136:139], v[184:187], v[72:75]
	v_mfma_f32_16x16x32_bf16 v[124:127], v[132:135], v[148:151], v[124:127]
	v_mfma_f32_16x16x32_bf16 v[120:123], v[140:143], v[148:151], v[120:123]
	v_mfma_f32_16x16x32_bf16 v[116:119], v[132:135], v[156:159], v[116:119]
	v_mfma_f32_16x16x32_bf16 v[104:107], v[140:143], v[156:159], v[104:107]
	v_mfma_f32_16x16x32_bf16 v[92:95], v[132:135], v[180:183], v[92:95]
	v_mfma_f32_16x16x32_bf16 v[88:91], v[140:143], v[180:183], v[88:91]
	v_mfma_f32_16x16x32_bf16 v[76:79], v[132:135], v[188:191], v[76:79]
	v_mfma_f32_16x16x32_bf16 v[72:75], v[140:143], v[188:191], v[72:75]
	v_mfma_f32_16x16x32_bf16 v[112:115], v[200:203], v[144:147], v[112:115]
	v_mfma_f32_16x16x32_bf16 v[108:111], v[208:211], v[144:147], v[108:111]
	v_mfma_f32_16x16x32_bf16 v[100:103], v[200:203], v[152:155], v[100:103]
	v_mfma_f32_16x16x32_bf16 v[96:99], v[208:211], v[152:155], v[96:99]
	v_mfma_f32_16x16x32_bf16 v[84:87], v[200:203], v[160:163], v[84:87]
	v_mfma_f32_16x16x32_bf16 v[80:83], v[208:211], v[160:163], v[80:83]
	v_mfma_f32_16x16x32_bf16 v[68:71], v[200:203], v[184:187], v[68:71]
	v_mfma_f32_16x16x32_bf16 v[64:67], v[208:211], v[184:187], v[64:67]
	v_mfma_f32_16x16x32_bf16 v[112:115], v[204:207], v[148:151], v[112:115]
	v_mfma_f32_16x16x32_bf16 v[108:111], v[212:215], v[148:151], v[108:111]
	v_mfma_f32_16x16x32_bf16 v[100:103], v[204:207], v[156:159], v[100:103]
	v_mfma_f32_16x16x32_bf16 v[96:99], v[212:215], v[156:159], v[96:99]
	v_mfma_f32_16x16x32_bf16 v[84:87], v[204:207], v[180:183], v[84:87]
	v_mfma_f32_16x16x32_bf16 v[80:83], v[212:215], v[180:183], v[80:83]
	v_mfma_f32_16x16x32_bf16 v[68:71], v[204:207], v[188:191], v[68:71]
	v_mfma_f32_16x16x32_bf16 v[64:67], v[212:215], v[188:191], v[64:67]
	s_barrier
	global_load_lds_dwordx4 v164, s[22:23]
	s_add_i32 m0, s29, 0x2000
	s_nop 0
	global_load_lds_dwordx4 v168, s[22:23]
	s_mov_b32 m0, s54
	v_lshl_add_u64 v[192:193], v[192:193], 0, s[12:13]
	ds_read_b128 v[144:147], v198 offset:49152
	ds_read_b128 v[148:151], v198 offset:50176
	ds_read_b128 v[152:155], v198 offset:51200
	ds_read_b128 v[156:159], v198 offset:52224
	ds_read_b128 v[160:163], v198 offset:53248
	ds_read_b128 v[180:183], v198 offset:54272
	ds_read_b128 v[184:187], v198 offset:55296
	ds_read_b128 v[188:191], v198 offset:56320
	global_load_lds_dwordx4 v[192:193], off
	v_lshl_add_u64 v[192:193], v[216:217], 0, s[12:13]
	s_mov_b32 m0, s55
	s_nop 0
	global_load_lds_dwordx4 v[192:193], off
	s_add_u32 s22, s26, 0xc000
	s_addc_u32 s23, s27, 0
	s_add_i32 s26, s28, s48
	s_mov_b32 m0, s26
	s_nop 0
	global_load_lds_dwordx4 v164, s[22:23]
	s_add_i32 m0, s26, 0x2000
	s_nop 0
	global_load_lds_dwordx4 v168, s[22:23]
	s_add_i32 s65, s65, 2
	s_add_u32 s63, s63, 0x10000
	s_addc_u32 s64, s64, 0
	s_cmpk_gt_u32 s65, 0x53
	s_mov_b64 s[22:23], s[24:25]
	s_waitcnt vmcnt(8)
	s_waitcnt lgkmcnt(0)
	s_barrier
	v_mfma_f32_16x16x32_bf16 v[60:63], v[128:131], v[144:147], v[60:63]
	v_mfma_f32_16x16x32_bf16 v[56:59], v[136:139], v[144:147], v[56:59]
	v_mfma_f32_16x16x32_bf16 v[44:47], v[128:131], v[152:155], v[44:47]
	v_mfma_f32_16x16x32_bf16 v[40:43], v[136:139], v[152:155], v[40:43]
	v_mfma_f32_16x16x32_bf16 v[28:31], v[128:131], v[160:163], v[28:31]
	v_mfma_f32_16x16x32_bf16 v[24:27], v[136:139], v[160:163], v[24:27]
	v_mfma_f32_16x16x32_bf16 v[12:15], v[128:131], v[184:187], v[12:15]
	v_mfma_f32_16x16x32_bf16 v[8:11], v[136:139], v[184:187], v[8:11]
	v_mfma_f32_16x16x32_bf16 v[60:63], v[132:135], v[148:151], v[60:63]
	v_mfma_f32_16x16x32_bf16 v[56:59], v[140:143], v[148:151], v[56:59]
	v_mfma_f32_16x16x32_bf16 v[44:47], v[132:135], v[156:159], v[44:47]
	v_mfma_f32_16x16x32_bf16 v[40:43], v[140:143], v[156:159], v[40:43]
	v_mfma_f32_16x16x32_bf16 v[28:31], v[132:135], v[180:183], v[28:31]
	v_mfma_f32_16x16x32_bf16 v[24:27], v[140:143], v[180:183], v[24:27]
	v_mfma_f32_16x16x32_bf16 v[12:15], v[132:135], v[188:191], v[12:15]
	v_mfma_f32_16x16x32_bf16 v[8:11], v[140:143], v[188:191], v[8:11]
	v_mfma_f32_16x16x32_bf16 v[52:55], v[200:203], v[144:147], v[52:55]
	v_mfma_f32_16x16x32_bf16 v[48:51], v[208:211], v[144:147], v[48:51]
	v_mfma_f32_16x16x32_bf16 v[36:39], v[200:203], v[152:155], v[36:39]
	v_mfma_f32_16x16x32_bf16 v[32:35], v[208:211], v[152:155], v[32:35]
	v_mfma_f32_16x16x32_bf16 v[20:23], v[200:203], v[160:163], v[20:23]
	v_mfma_f32_16x16x32_bf16 v[16:19], v[208:211], v[160:163], v[16:19]
	v_mfma_f32_16x16x32_bf16 v[4:7], v[200:203], v[184:187], v[4:7]
	v_mfma_f32_16x16x32_bf16 v[0:3], v[208:211], v[184:187], v[0:3]
	v_mfma_f32_16x16x32_bf16 v[52:55], v[204:207], v[148:151], v[52:55]
	v_mfma_f32_16x16x32_bf16 v[48:51], v[212:215], v[148:151], v[48:51]
	v_mfma_f32_16x16x32_bf16 v[36:39], v[204:207], v[156:159], v[36:39]
	v_mfma_f32_16x16x32_bf16 v[32:35], v[212:215], v[156:159], v[32:35]
	v_mfma_f32_16x16x32_bf16 v[20:23], v[204:207], v[180:183], v[20:23]
	v_mfma_f32_16x16x32_bf16 v[16:19], v[212:215], v[180:183], v[16:19]
	v_mfma_f32_16x16x32_bf16 v[4:7], v[204:207], v[188:191], v[4:7]
	v_mfma_f32_16x16x32_bf16 v[0:3], v[212:215], v[188:191], v[0:3]
	s_cbranch_scc1 .Lunit_exit_7
	s_barrier
	s_branch .LBB0_980
